# knorm loop unrolled x2 with double-buffered prefetch: next 4-row batch's loads issued before the current batch is reduced (conservative vmcnt(12) waits); bit-identical; on top of the knorm relayout
# speedup vs baseline: 1.0126x; 1.0071x over previous
; __device__ __forceinline__ float bf2f(unsigned short u) { return __uint_as_float((unsigned)u << 16); }
; __device__ __forceinline__ void knorm_item(const KArgs& a, int l, int item, int wave, int lane) {
;     const bf16_t* Z = (const bf16_t*)(a.ws + WS_Z);
;     const float kg = a.in[I_KN][l * 64 + lane];
;     for (int r0 = 0; r0 < 128; r0 += 16) {
;         float v[16];
; #pragma unroll
;         for (int i = 0; i < 16; ++i) { const int task = item * 1024 + wave * 128 + r0 + i, row = task >> 2, which = (task >> 1) & 1, g = task & 1;
;             v[i] = bf2f(Z[(size_t)row * ZW + (which ? ZC_KW : ZC_KS) + g * 64 + lane]); }
; __device__ __forceinline__ void phase_mix1(const KArgs& a, int l, LAS unsigned char* lds, int wave, int lane, int ci) {
;     ...
;     for (;;) {
;         __syncthreads();
;         if (threadIdx.x == 0) *slot = (int)atomicAdd(ctr, 1u);
;         __syncthreads();
;         int r = *slot;
;         if (r >= N_R0 + N_CMP + N_CONV + N_KN) break;
;         if (r < N_R0) { ret0_item(a, l, r, lds, wave, lane); continue; } r -= N_R0;
;         if (r < N_CMP) { cmp_mfma_item(a, l, r, lds, wave, lane); continue; } r -= N_CMP;
;         if (r < N_CONV) { conv_item(a, l, r); continue; } r -= N_CONV;
;         knorm_item(a, l, r, wave, lane);
.LBB0_232:
	s_or_b64 exec, exec, s[0:1]
	s_waitcnt lgkmcnt(0)
	s_barrier
	ds_read_b32 v0, v120
	s_movk_i32 s0, 0x2ff
	s_waitcnt lgkmcnt(0)
	v_cmp_lt_i32_e32 vcc, s0, v0
	v_readfirstlane_b32 s33, v0
	s_mov_b64 s[0:1], -1
	s_cbranch_vccnz .LBB0_227
	s_cmpk_gt_i32 s33, 0x7f
	s_cbranch_scc0 .LBB0_262
	s_cmpk_gt_u32 s33, 0xff
	s_cbranch_scc0 .LBB0_243
	s_cmpk_gt_u32 s33, 0x1ff
	s_cbranch_scc0 .LBB0_239
	global_load_dword v8, v[66:67], off
	v_cmp_lt_i32_e32 vcc, v124, v123
	s_lshl_b32 s0, s33, 10
	s_add_i32 s24, s34, s0
	v_cndmask_b32_e32 v0, v122, v124, vcc
	v_cmp_lt_i32_e32 vcc, v125, v123
	v_lshlrev_b32_e32 v9, 2, v0
	s_mov_b32 s57, -16
	v_cndmask_b32_e32 v0, v122, v125, vcc
	v_cmp_lt_i32_e32 vcc, v126, v123
	v_lshlrev_b32_e32 v10, 2, v0
	s_nop 0
	v_cndmask_b32_e32 v0, v122, v126, vcc
	v_cmp_lt_i32_e32 vcc, v127, v123
	v_lshlrev_b32_e32 v11, 2, v0
	s_nop 0
	v_cndmask_b32_e32 v0, v122, v127, vcc
	v_cmp_lt_i32_e32 vcc, v128, v123
	v_lshlrev_b32_e32 v12, 2, v0
	s_nop 0
	v_cndmask_b32_e32 v0, v122, v128, vcc
	v_cmp_lt_i32_e32 vcc, v129, v123
	v_lshlrev_b32_e32 v13, 2, v0
	s_nop 0
	v_cndmask_b32_e32 v0, v122, v129, vcc
	v_lshlrev_b32_e32 v14, 2, v0
	v_mbcnt_lo_u32_b32 v186, -1, 0
	v_mbcnt_hi_u32_b32 v186, -1, v186
	v_and_b32_e32 v188, 31, v186
	v_lshlrev_b32_e32 v188, 3, v188
	v_lshlrev_b32_e32 v187, 2, v186
	v_sub_u32_e32 v188, v188, v187
	v_ashrrev_i32_e32 v189, 31, v188
	v_lshl_add_u64 v[188:189], v[66:67], 0, v[188:189]
	global_load_dwordx2 v[184:185], v[188:189], off
	v_lshlrev_b32_e32 v186, 1, v186
	v_mov_b32_e32 v187, 0
	v_lshl_add_u64 v[190:191], v[68:69], 0, v[186:187]
	v_lshl_add_u64 v[192:193], v[70:71], 0, v[186:187]
	v_mov_b32_e32 v194, 0x7060302
	v_mov_b32_e32 v195, s20
	v_lshl_add_u64 v[196:197], v[64:65], 0, v[186:187]
	v_mov_b32_e32 v198, s47
	v_mov_b32_e32 v199, 0
	v_lshl_add_u64 v[196:197], v[196:197], 0, v[198:199]
	s_add_i32 s0, s24, s57
	s_add_i32 s0, s0, 0xfff80010
	s_ashr_i32 s4, s0, 2
	s_ashr_i32 s5, s4, 31
	s_mul_i32 s0, s4, 0x1a00
	s_mul_hi_i32 s1, s4, 0x1a00
	s_add_u32 s0, s92, s0
	s_addc_u32 s1, s93, s1
	v_lshl_add_u64 v[0:1], s[0:1], 0, v[196:197]
	global_load_dword v4, v[0:1], off offset:1024
	global_load_dword v6, v[0:1], off offset:1536
	s_add_u32 s0, s0, 0x1a00
	s_addc_u32 s1, s1, 0
	v_lshl_add_u64 v[2:3], s[0:1], 0, v[196:197]
	global_load_dword v27, v[2:3], off offset:1024
	global_load_dword v28, v[2:3], off offset:1536
	s_add_u32 s0, s0, 0x1a00
	s_addc_u32 s1, s1, 0
	v_lshl_add_u64 v[0:1], s[0:1], 0, v[196:197]
	global_load_dword v25, v[0:1], off offset:1024
	global_load_dword v26, v[0:1], off offset:1536
	s_add_u32 s0, s0, 0x1a00
	s_addc_u32 s1, s1, 0
	v_lshl_add_u64 v[2:3], s[0:1], 0, v[196:197]
	global_load_dword v23, v[2:3], off offset:1024
	global_load_dword v24, v[2:3], off offset:1536
.LBB0_237:
	s_add_i32 s0, s24, s57
	s_add_i32 s0, s0, 0xfff80020
	s_ashr_i32 s4, s0, 2
	s_ashr_i32 s5, s4, 31
	s_mul_i32 s0, s4, 0x1a00
	s_mul_hi_i32 s1, s4, 0x1a00
	s_add_u32 s0, s92, s0
	s_addc_u32 s1, s93, s1
	v_lshl_add_u64 v[0:1], s[0:1], 0, v[196:197]
	global_load_dword v21, v[0:1], off offset:1024
	global_load_dword v22, v[0:1], off offset:1536
	s_add_u32 s0, s0, 0x1a00
	s_addc_u32 s1, s1, 0
	v_lshl_add_u64 v[2:3], s[0:1], 0, v[196:197]
	global_load_dword v19, v[2:3], off offset:1024
	global_load_dword v20, v[2:3], off offset:1536
	s_add_u32 s0, s0, 0x1a00
	s_addc_u32 s1, s1, 0
	v_lshl_add_u64 v[0:1], s[0:1], 0, v[196:197]
	global_load_dword v17, v[0:1], off offset:1024
	global_load_dword v18, v[0:1], off offset:1536
	s_add_u32 s0, s0, 0x1a00
	s_addc_u32 s1, s1, 0
	v_lshl_add_u64 v[2:3], s[0:1], 0, v[196:197]
	global_load_dword v15, v[2:3], off offset:1024
	global_load_dword v16, v[2:3], off offset:1536
	s_add_i32 s0, s24, s57
	s_add_i32 s0, s0, 0xfff80010
	s_ashr_i32 s4, s0, 2
	s_ashr_i32 s5, s4, 31
	s_lshl_b64 s[30:31], s[4:5], 8
	v_lshl_add_u64 v[200:201], v[190:191], 0, s[30:31]
	v_lshl_add_u64 v[202:203], v[192:193], 0, s[30:31]
	s_waitcnt vmcnt(12)
	v_lshlrev_b32_e32 v220, 16, v4
	v_and_b32_e32 v221, 0xffff0000, v4
	v_lshlrev_b32_e32 v228, 16, v6
	v_and_b32_e32 v229, 0xffff0000, v6
	v_lshlrev_b32_e32 v236, 16, v27
	v_and_b32_e32 v237, 0xffff0000, v27
	v_lshlrev_b32_e32 v244, 16, v28
	v_and_b32_e32 v245, 0xffff0000, v28
	v_mul_f32_e32 v224, v220, v220
	v_mul_f32_e32 v225, v221, v221
	v_mul_f32_e32 v232, v228, v228
	v_mul_f32_e32 v233, v229, v229
	v_mul_f32_e32 v240, v236, v236
	v_mul_f32_e32 v241, v237, v237
	v_mul_f32_e32 v248, v244, v244
	v_mul_f32_e32 v249, v245, v245
	v_fma_f32 v222, v220, v220, v225
	v_fma_f32 v223, v221, v221, v224
	v_fma_f32 v230, v228, v228, v233
	v_fma_f32 v231, v229, v229, v232
	v_fma_f32 v238, v236, v236, v241
	v_fma_f32 v239, v237, v237, v240
	v_fma_f32 v246, v244, v244, v249
	v_fma_f32 v247, v245, v245, v248
	v_add_f32_dpp v222, v222, v222 quad_perm:[1,0,3,2] row_mask:0xf bank_mask:0xf
	v_add_f32_dpp v223, v223, v223 quad_perm:[1,0,3,2] row_mask:0xf bank_mask:0xf
	v_add_f32_dpp v230, v230, v230 quad_perm:[1,0,3,2] row_mask:0xf bank_mask:0xf
	v_add_f32_dpp v231, v231, v231 quad_perm:[1,0,3,2] row_mask:0xf bank_mask:0xf
	v_add_f32_dpp v238, v238, v238 quad_perm:[1,0,3,2] row_mask:0xf bank_mask:0xf
	v_add_f32_dpp v239, v239, v239 quad_perm:[1,0,3,2] row_mask:0xf bank_mask:0xf
	v_add_f32_dpp v246, v246, v246 quad_perm:[1,0,3,2] row_mask:0xf bank_mask:0xf
	v_add_f32_dpp v247, v247, v247 quad_perm:[1,0,3,2] row_mask:0xf bank_mask:0xf
	v_add_f32_dpp v222, v222, v222 quad_perm:[2,3,0,1] row_mask:0xf bank_mask:0xf
	v_add_f32_dpp v223, v223, v223 quad_perm:[2,3,0,1] row_mask:0xf bank_mask:0xf
	v_add_f32_dpp v230, v230, v230 quad_perm:[2,3,0,1] row_mask:0xf bank_mask:0xf
	v_add_f32_dpp v231, v231, v231 quad_perm:[2,3,0,1] row_mask:0xf bank_mask:0xf
	v_add_f32_dpp v238, v238, v238 quad_perm:[2,3,0,1] row_mask:0xf bank_mask:0xf
	v_add_f32_dpp v239, v239, v239 quad_perm:[2,3,0,1] row_mask:0xf bank_mask:0xf
	v_add_f32_dpp v246, v246, v246 quad_perm:[2,3,0,1] row_mask:0xf bank_mask:0xf
	v_add_f32_dpp v247, v247, v247 quad_perm:[2,3,0,1] row_mask:0xf bank_mask:0xf
	ds_bpermute_b32 v224, v11, v222
	ds_bpermute_b32 v225, v11, v223
	ds_bpermute_b32 v232, v11, v230
	ds_bpermute_b32 v233, v11, v231
	ds_bpermute_b32 v240, v11, v238
	ds_bpermute_b32 v241, v11, v239
	ds_bpermute_b32 v248, v11, v246
	ds_bpermute_b32 v249, v11, v247
	s_waitcnt lgkmcnt(0)
; __device__ __forceinline__ float bf2f(unsigned short u) { return __uint_as_float((unsigned)u << 16); }
; __device__ __forceinline__ unsigned f2bf(float f) { unsigned u = __float_as_uint(f); return (u + 0x7fffu + ((u >> 16) & 1u)) >> 16; }
; __device__ __forceinline__ void knorm_item(const KArgs& a, int l, int item, int wave, int lane) {
;     ...
;         for (int i = 0; i < 16; ++i) { const int task = item * 1024 + wave * 128 + r0 + i, row = task >> 2, which = (task >> 1) & 1, g = task & 1;
;             v[i] = bf2f(Z[(size_t)row * ZW + (which ? ZC_KW : ZC_KS) + g * 64 + lane]); }
; #pragma unroll
;         for (int i = 0; i < 16; ++i) { const int task = item * 1024 + wave * 128 + r0 + i, row = task >> 2, which = (task >> 1) & 1, g = task & 1;
;             const float rstd = rsqrtf(wave_sum(v[i] * v[i]) * (1.f / 64.f) + EPS);
;             bf16_t* dst = (bf16_t*)(a.ws + (which ? WS_KWN : WS_KSN));
;             dst[(size_t)row * 128 + g * 64 + lane] = (bf16_t)f2bf(v[i] * rstd * kg); }
	v_add_f32_e32 v222, v222, v224
	v_add_f32_e32 v223, v223, v225
	v_add_f32_e32 v230, v230, v232
	v_add_f32_e32 v231, v231, v233
	v_add_f32_e32 v238, v238, v240
	v_add_f32_e32 v239, v239, v241
	v_add_f32_e32 v246, v246, v248
	v_add_f32_e32 v247, v247, v249
	v_add_f32_dpp v222, v222, v222 row_ror:8 row_mask:0xf bank_mask:0xf
	v_add_f32_dpp v223, v223, v223 row_ror:8 row_mask:0xf bank_mask:0xf
	v_add_f32_dpp v230, v230, v230 row_ror:8 row_mask:0xf bank_mask:0xf
	v_add_f32_dpp v231, v231, v231 row_ror:8 row_mask:0xf bank_mask:0xf
	v_add_f32_dpp v238, v238, v238 row_ror:8 row_mask:0xf bank_mask:0xf
	v_add_f32_dpp v239, v239, v239 row_ror:8 row_mask:0xf bank_mask:0xf
	v_add_f32_dpp v246, v246, v246 row_ror:8 row_mask:0xf bank_mask:0xf
	v_add_f32_dpp v247, v247, v247 row_ror:8 row_mask:0xf bank_mask:0xf
	ds_bpermute_b32 v224, v13, v222
	ds_bpermute_b32 v225, v13, v223
	ds_bpermute_b32 v232, v13, v230
	ds_bpermute_b32 v233, v13, v231
	ds_bpermute_b32 v240, v13, v238
	ds_bpermute_b32 v241, v13, v239
	ds_bpermute_b32 v248, v13, v246
	ds_bpermute_b32 v249, v13, v247
	s_waitcnt lgkmcnt(0)
	v_add_f32_e32 v222, v222, v224
	v_add_f32_e32 v223, v223, v225
	v_add_f32_e32 v230, v230, v232
	v_add_f32_e32 v231, v231, v233
	v_add_f32_e32 v238, v238, v240
	v_add_f32_e32 v239, v239, v241
	v_add_f32_e32 v246, v246, v248
	v_add_f32_e32 v247, v247, v249
	v_fma_f32 v222, v222, s22, v195
	v_fma_f32 v223, v223, s22, v195
	v_fma_f32 v230, v230, s22, v195
	v_fma_f32 v231, v231, s22, v195
	v_fma_f32 v238, v238, s22, v195
	v_fma_f32 v239, v239, s22, v195
	v_fma_f32 v246, v246, s22, v195
	v_fma_f32 v247, v247, s22, v195
	v_mul_f32_e32 v226, 0x4b800000, v222
	    v_mul_f32_e32 v227, 0x4b800000, v223
	    v_cmp_gt_f32_e64 s[4:5], s48, v222
	    v_cmp_gt_f32_e32 vcc, s48, v223
	    s_nop 1
	    v_cndmask_b32_e64 v222, v222, v226, s[4:5]
	    v_cndmask_b32_e32 v223, v223, v227, vcc
	    v_rsq_f32_e32 v222, v222
	    v_rsq_f32_e32 v223, v223
	    s_nop 0
	    v_mul_f32_e32 v226, 0x45800000, v222
	    v_mul_f32_e32 v227, 0x45800000, v223
	    v_cndmask_b32_e64 v222, v222, v226, s[4:5]
	    v_cndmask_b32_e32 v223, v223, v227, vcc
	    v_mul_f32_e32 v220, v222, v220
	    v_mul_f32_e32 v221, v223, v221
	    v_mul_f32_e32 v220, v184, v220
	    v_mul_f32_e32 v221, v185, v221
	    v_bfe_u32 v226, v220, 16, 1
	    v_bfe_u32 v227, v221, 16, 1
	    v_add3_u32 v220, v220, v226, s49
	    v_add3_u32 v221, v221, v227, s49
	    v_perm_b32 v4, v221, v220, v194
	    global_store_dword v[200:201], v4, off
	v_mul_f32_e32 v234, 0x4b800000, v230
	    v_mul_f32_e32 v235, 0x4b800000, v231
	    v_cmp_gt_f32_e64 s[4:5], s48, v230
	    v_cmp_gt_f32_e32 vcc, s48, v231
	    s_nop 1
	    v_cndmask_b32_e64 v230, v230, v234, s[4:5]
	    v_cndmask_b32_e32 v231, v231, v235, vcc
	    v_rsq_f32_e32 v230, v230
	    v_rsq_f32_e32 v231, v231
	    s_nop 0
	    v_mul_f32_e32 v234, 0x45800000, v230
	    v_mul_f32_e32 v235, 0x45800000, v231
	    v_cndmask_b32_e64 v230, v230, v234, s[4:5]
	    v_cndmask_b32_e32 v231, v231, v235, vcc
	    v_mul_f32_e32 v228, v230, v228
	    v_mul_f32_e32 v229, v231, v229
	    v_mul_f32_e32 v228, v184, v228
	    v_mul_f32_e32 v229, v185, v229
	    v_bfe_u32 v234, v228, 16, 1
	    v_bfe_u32 v235, v229, 16, 1
	    v_add3_u32 v228, v228, v234, s49
	    v_add3_u32 v229, v229, v235, s49
	    v_perm_b32 v6, v229, v228, v194
	    global_store_dword v[202:203], v6, off
	v_mul_f32_e32 v242, 0x4b800000, v238
	    v_mul_f32_e32 v243, 0x4b800000, v239
	    v_cmp_gt_f32_e64 s[4:5], s48, v238
	    v_cmp_gt_f32_e32 vcc, s48, v239
	    s_nop 1
	    v_cndmask_b32_e64 v238, v238, v242, s[4:5]
	    v_cndmask_b32_e32 v239, v239, v243, vcc
	    v_rsq_f32_e32 v238, v238
	    v_rsq_f32_e32 v239, v239
	    s_nop 0
	    v_mul_f32_e32 v242, 0x45800000, v238
	    v_mul_f32_e32 v243, 0x45800000, v239
	    v_cndmask_b32_e64 v238, v238, v242, s[4:5]
	    v_cndmask_b32_e32 v239, v239, v243, vcc
	    v_mul_f32_e32 v236, v238, v236
	    v_mul_f32_e32 v237, v239, v237
	    v_mul_f32_e32 v236, v184, v236
	    v_mul_f32_e32 v237, v185, v237
	    v_bfe_u32 v242, v236, 16, 1
	    v_bfe_u32 v243, v237, 16, 1
	    v_add3_u32 v236, v236, v242, s49
	    v_add3_u32 v237, v237, v243, s49
	    v_perm_b32 v27, v237, v236, v194
	    global_store_dword v[200:201], v27, off offset:256
	v_mul_f32_e32 v250, 0x4b800000, v246
	    v_mul_f32_e32 v251, 0x4b800000, v247
	    v_cmp_gt_f32_e64 s[4:5], s48, v246
	    v_cmp_gt_f32_e32 vcc, s48, v247
	    s_nop 1
	    v_cndmask_b32_e64 v246, v246, v250, s[4:5]
	    v_cndmask_b32_e32 v247, v247, v251, vcc
	    v_rsq_f32_e32 v246, v246
	    v_rsq_f32_e32 v247, v247
	    s_nop 0
	    v_mul_f32_e32 v250, 0x45800000, v246
	    v_mul_f32_e32 v251, 0x45800000, v247
	    v_cndmask_b32_e64 v246, v246, v250, s[4:5]
	    v_cndmask_b32_e32 v247, v247, v251, vcc
	    v_mul_f32_e32 v244, v246, v244
	    v_mul_f32_e32 v245, v247, v245
	    v_mul_f32_e32 v244, v184, v244
	    v_mul_f32_e32 v245, v185, v245
	    v_bfe_u32 v250, v244, 16, 1
	    v_bfe_u32 v251, v245, 16, 1
	    v_add3_u32 v244, v244, v250, s49
	    v_add3_u32 v245, v245, v251, s49
	    v_perm_b32 v28, v245, v244, v194
	    global_store_dword v[202:203], v28, off offset:256
	s_waitcnt vmcnt(12)
; __device__ __forceinline__ float bf2f(unsigned short u) { return __uint_as_float((unsigned)u << 16); }
; __device__ __forceinline__ unsigned f2bf(float f) { unsigned u = __float_as_uint(f); return (u + 0x7fffu + ((u >> 16) & 1u)) >> 16; }
; __device__ __forceinline__ void knorm_item(const KArgs& a, int l, int item, int wave, int lane) {
;     ...
;         for (int i = 0; i < 16; ++i) { const int task = item * 1024 + wave * 128 + r0 + i, row = task >> 2, which = (task >> 1) & 1, g = task & 1;
;             v[i] = bf2f(Z[(size_t)row * ZW + (which ? ZC_KW : ZC_KS) + g * 64 + lane]); }
; #pragma unroll
;         for (int i = 0; i < 16; ++i) { const int task = item * 1024 + wave * 128 + r0 + i, row = task >> 2, which = (task >> 1) & 1, g = task & 1;
;             const float rstd = rsqrtf(wave_sum(v[i] * v[i]) * (1.f / 64.f) + EPS);
;             bf16_t* dst = (bf16_t*)(a.ws + (which ? WS_KWN : WS_KSN));
;             dst[(size_t)row * 128 + g * 64 + lane] = (bf16_t)f2bf(v[i] * rstd * kg); }
	v_lshlrev_b32_e32 v220, 16, v25
	v_and_b32_e32 v221, 0xffff0000, v25
	v_lshlrev_b32_e32 v228, 16, v26
	v_and_b32_e32 v229, 0xffff0000, v26
	v_lshlrev_b32_e32 v236, 16, v23
	v_and_b32_e32 v237, 0xffff0000, v23
	v_lshlrev_b32_e32 v244, 16, v24
	v_and_b32_e32 v245, 0xffff0000, v24
	v_mul_f32_e32 v224, v220, v220
	v_mul_f32_e32 v225, v221, v221
	v_mul_f32_e32 v232, v228, v228
	v_mul_f32_e32 v233, v229, v229
	v_mul_f32_e32 v240, v236, v236
	v_mul_f32_e32 v241, v237, v237
	v_mul_f32_e32 v248, v244, v244
	v_mul_f32_e32 v249, v245, v245
	v_fma_f32 v222, v220, v220, v225
	v_fma_f32 v223, v221, v221, v224
	v_fma_f32 v230, v228, v228, v233
	v_fma_f32 v231, v229, v229, v232
	v_fma_f32 v238, v236, v236, v241
	v_fma_f32 v239, v237, v237, v240
	v_fma_f32 v246, v244, v244, v249
	v_fma_f32 v247, v245, v245, v248
	v_add_f32_dpp v222, v222, v222 quad_perm:[1,0,3,2] row_mask:0xf bank_mask:0xf
	v_add_f32_dpp v223, v223, v223 quad_perm:[1,0,3,2] row_mask:0xf bank_mask:0xf
	v_add_f32_dpp v230, v230, v230 quad_perm:[1,0,3,2] row_mask:0xf bank_mask:0xf
	v_add_f32_dpp v231, v231, v231 quad_perm:[1,0,3,2] row_mask:0xf bank_mask:0xf
	v_add_f32_dpp v238, v238, v238 quad_perm:[1,0,3,2] row_mask:0xf bank_mask:0xf
	v_add_f32_dpp v239, v239, v239 quad_perm:[1,0,3,2] row_mask:0xf bank_mask:0xf
	v_add_f32_dpp v246, v246, v246 quad_perm:[1,0,3,2] row_mask:0xf bank_mask:0xf
	v_add_f32_dpp v247, v247, v247 quad_perm:[1,0,3,2] row_mask:0xf bank_mask:0xf
	v_add_f32_dpp v222, v222, v222 quad_perm:[2,3,0,1] row_mask:0xf bank_mask:0xf
	v_add_f32_dpp v223, v223, v223 quad_perm:[2,3,0,1] row_mask:0xf bank_mask:0xf
	v_add_f32_dpp v230, v230, v230 quad_perm:[2,3,0,1] row_mask:0xf bank_mask:0xf
	v_add_f32_dpp v231, v231, v231 quad_perm:[2,3,0,1] row_mask:0xf bank_mask:0xf
	v_add_f32_dpp v238, v238, v238 quad_perm:[2,3,0,1] row_mask:0xf bank_mask:0xf
	v_add_f32_dpp v239, v239, v239 quad_perm:[2,3,0,1] row_mask:0xf bank_mask:0xf
	v_add_f32_dpp v246, v246, v246 quad_perm:[2,3,0,1] row_mask:0xf bank_mask:0xf
	v_add_f32_dpp v247, v247, v247 quad_perm:[2,3,0,1] row_mask:0xf bank_mask:0xf
	ds_bpermute_b32 v224, v11, v222
	ds_bpermute_b32 v225, v11, v223
	ds_bpermute_b32 v232, v11, v230
	ds_bpermute_b32 v233, v11, v231
	ds_bpermute_b32 v240, v11, v238
	ds_bpermute_b32 v241, v11, v239
	ds_bpermute_b32 v248, v11, v246
	ds_bpermute_b32 v249, v11, v247
	s_waitcnt lgkmcnt(0)
	v_add_f32_e32 v222, v222, v224
	v_add_f32_e32 v223, v223, v225
	v_add_f32_e32 v230, v230, v232
	v_add_f32_e32 v231, v231, v233
	v_add_f32_e32 v238, v238, v240
	v_add_f32_e32 v239, v239, v241
	v_add_f32_e32 v246, v246, v248
	v_add_f32_e32 v247, v247, v249
	v_add_f32_dpp v222, v222, v222 row_ror:8 row_mask:0xf bank_mask:0xf
	v_add_f32_dpp v223, v223, v223 row_ror:8 row_mask:0xf bank_mask:0xf
	v_add_f32_dpp v230, v230, v230 row_ror:8 row_mask:0xf bank_mask:0xf
	v_add_f32_dpp v231, v231, v231 row_ror:8 row_mask:0xf bank_mask:0xf
	v_add_f32_dpp v238, v238, v238 row_ror:8 row_mask:0xf bank_mask:0xf
	v_add_f32_dpp v239, v239, v239 row_ror:8 row_mask:0xf bank_mask:0xf
	v_add_f32_dpp v246, v246, v246 row_ror:8 row_mask:0xf bank_mask:0xf
	v_add_f32_dpp v247, v247, v247 row_ror:8 row_mask:0xf bank_mask:0xf
	ds_bpermute_b32 v224, v13, v222
	ds_bpermute_b32 v225, v13, v223
	ds_bpermute_b32 v232, v13, v230
	ds_bpermute_b32 v233, v13, v231
	ds_bpermute_b32 v240, v13, v238
	ds_bpermute_b32 v241, v13, v239
	ds_bpermute_b32 v248, v13, v246
	ds_bpermute_b32 v249, v13, v247
	s_waitcnt lgkmcnt(0)
	v_add_f32_e32 v222, v222, v224
	v_add_f32_e32 v223, v223, v225
	v_add_f32_e32 v230, v230, v232
	v_add_f32_e32 v231, v231, v233
	v_add_f32_e32 v238, v238, v240
	v_add_f32_e32 v239, v239, v241
	v_add_f32_e32 v246, v246, v248
	v_add_f32_e32 v247, v247, v249
	v_fma_f32 v222, v222, s22, v195
	v_fma_f32 v223, v223, s22, v195
	v_fma_f32 v230, v230, s22, v195
	v_fma_f32 v231, v231, s22, v195
	v_fma_f32 v238, v238, s22, v195
	v_fma_f32 v239, v239, s22, v195
	v_fma_f32 v246, v246, s22, v195
	v_fma_f32 v247, v247, s22, v195
	v_mul_f32_e32 v226, 0x4b800000, v222
	    v_mul_f32_e32 v227, 0x4b800000, v223
	    v_cmp_gt_f32_e64 s[4:5], s48, v222
	    v_cmp_gt_f32_e32 vcc, s48, v223
	    s_nop 1
	    v_cndmask_b32_e64 v222, v222, v226, s[4:5]
	    v_cndmask_b32_e32 v223, v223, v227, vcc
	    v_rsq_f32_e32 v222, v222
	    v_rsq_f32_e32 v223, v223
	    s_nop 0
	    v_mul_f32_e32 v226, 0x45800000, v222
	    v_mul_f32_e32 v227, 0x45800000, v223
	    v_cndmask_b32_e64 v222, v222, v226, s[4:5]
	    v_cndmask_b32_e32 v223, v223, v227, vcc
	    v_mul_f32_e32 v220, v222, v220
	    v_mul_f32_e32 v221, v223, v221
	    v_mul_f32_e32 v220, v184, v220
	    v_mul_f32_e32 v221, v185, v221
	    v_bfe_u32 v226, v220, 16, 1
	    v_bfe_u32 v227, v221, 16, 1
	    v_add3_u32 v220, v220, v226, s49
	    v_add3_u32 v221, v221, v227, s49
	    v_perm_b32 v25, v221, v220, v194
	    global_store_dword v[200:201], v25, off offset:512
	v_mul_f32_e32 v234, 0x4b800000, v230
	    v_mul_f32_e32 v235, 0x4b800000, v231
	    v_cmp_gt_f32_e64 s[4:5], s48, v230
	    v_cmp_gt_f32_e32 vcc, s48, v231
	    s_nop 1
	    v_cndmask_b32_e64 v230, v230, v234, s[4:5]
	    v_cndmask_b32_e32 v231, v231, v235, vcc
	    v_rsq_f32_e32 v230, v230
	    v_rsq_f32_e32 v231, v231
	    s_nop 0
	    v_mul_f32_e32 v234, 0x45800000, v230
	    v_mul_f32_e32 v235, 0x45800000, v231
	    v_cndmask_b32_e64 v230, v230, v234, s[4:5]
	    v_cndmask_b32_e32 v231, v231, v235, vcc
	    v_mul_f32_e32 v228, v230, v228
	    v_mul_f32_e32 v229, v231, v229
	    v_mul_f32_e32 v228, v184, v228
	    v_mul_f32_e32 v229, v185, v229
	    v_bfe_u32 v234, v228, 16, 1
	    v_bfe_u32 v235, v229, 16, 1
	    v_add3_u32 v228, v228, v234, s49
; __device__ __forceinline__ float bf2f(unsigned short u) { return __uint_as_float((unsigned)u << 16); }
; __device__ __forceinline__ unsigned f2bf(float f) { unsigned u = __float_as_uint(f); return (u + 0x7fffu + ((u >> 16) & 1u)) >> 16; }
; __device__ __forceinline__ void knorm_item(const KArgs& a, int l, int item, int wave, int lane) {
;     ...
;     for (int r0 = 0; r0 < 128; r0 += 16) {
;         float v[16];
; #pragma unroll
;         for (int i = 0; i < 16; ++i) { const int task = item * 1024 + wave * 128 + r0 + i, row = task >> 2, which = (task >> 1) & 1, g = task & 1;
;             v[i] = bf2f(Z[(size_t)row * ZW + (which ? ZC_KW : ZC_KS) + g * 64 + lane]); }
;     ...
;             const float rstd = rsqrtf(wave_sum(v[i] * v[i]) * (1.f / 64.f) + EPS);
;             bf16_t* dst = (bf16_t*)(a.ws + (which ? WS_KWN : WS_KSN));
;             dst[(size_t)row * 128 + g * 64 + lane] = (bf16_t)f2bf(v[i] * rstd * kg); }
	    v_add3_u32 v229, v229, v235, s49
	    v_perm_b32 v26, v229, v228, v194
	    global_store_dword v[202:203], v26, off offset:512
	v_mul_f32_e32 v242, 0x4b800000, v238
	    v_mul_f32_e32 v243, 0x4b800000, v239
	    v_cmp_gt_f32_e64 s[4:5], s48, v238
	    v_cmp_gt_f32_e32 vcc, s48, v239
	    s_nop 1
	    v_cndmask_b32_e64 v238, v238, v242, s[4:5]
	    v_cndmask_b32_e32 v239, v239, v243, vcc
	    v_rsq_f32_e32 v238, v238
	    v_rsq_f32_e32 v239, v239
	    s_nop 0
	    v_mul_f32_e32 v242, 0x45800000, v238
	    v_mul_f32_e32 v243, 0x45800000, v239
	    v_cndmask_b32_e64 v238, v238, v242, s[4:5]
	    v_cndmask_b32_e32 v239, v239, v243, vcc
	    v_mul_f32_e32 v236, v238, v236
	    v_mul_f32_e32 v237, v239, v237
	    v_mul_f32_e32 v236, v184, v236
	    v_mul_f32_e32 v237, v185, v237
	    v_bfe_u32 v242, v236, 16, 1
	    v_bfe_u32 v243, v237, 16, 1
	    v_add3_u32 v236, v236, v242, s49
	    v_add3_u32 v237, v237, v243, s49
	    v_perm_b32 v23, v237, v236, v194
	    global_store_dword v[200:201], v23, off offset:768
	v_mul_f32_e32 v250, 0x4b800000, v246
	    v_mul_f32_e32 v251, 0x4b800000, v247
	    v_cmp_gt_f32_e64 s[4:5], s48, v246
	    v_cmp_gt_f32_e32 vcc, s48, v247
	    s_nop 1
	    v_cndmask_b32_e64 v246, v246, v250, s[4:5]
	    v_cndmask_b32_e32 v247, v247, v251, vcc
	    v_rsq_f32_e32 v246, v246
	    v_rsq_f32_e32 v247, v247
	    s_nop 0
	    v_mul_f32_e32 v250, 0x45800000, v246
	    v_mul_f32_e32 v251, 0x45800000, v247
	    v_cndmask_b32_e64 v246, v246, v250, s[4:5]
	    v_cndmask_b32_e32 v247, v247, v251, vcc
	    v_mul_f32_e32 v244, v246, v244
	    v_mul_f32_e32 v245, v247, v245
	    v_mul_f32_e32 v244, v184, v244
	    v_mul_f32_e32 v245, v185, v245
	    v_bfe_u32 v250, v244, 16, 1
	    v_bfe_u32 v251, v245, 16, 1
	    v_add3_u32 v244, v244, v250, s49
	    v_add3_u32 v245, v245, v251, s49
	    v_perm_b32 v24, v245, v244, v194
	    global_store_dword v[202:203], v24, off offset:768
	s_cmpk_gt_i32 s57, 64
	s_cbranch_scc1 .Lkn3_skip_237
	s_add_i32 s0, s24, s57
	s_add_i32 s0, s0, 0xfff80030
	s_ashr_i32 s4, s0, 2
	s_ashr_i32 s5, s4, 31
	s_mul_i32 s0, s4, 0x1a00
	s_mul_hi_i32 s1, s4, 0x1a00
	s_add_u32 s0, s92, s0
	s_addc_u32 s1, s93, s1
	v_lshl_add_u64 v[0:1], s[0:1], 0, v[196:197]
	global_load_dword v4, v[0:1], off offset:1024
	global_load_dword v6, v[0:1], off offset:1536
	s_add_u32 s0, s0, 0x1a00
	s_addc_u32 s1, s1, 0
	v_lshl_add_u64 v[2:3], s[0:1], 0, v[196:197]
	global_load_dword v27, v[2:3], off offset:1024
	global_load_dword v28, v[2:3], off offset:1536
	s_add_u32 s0, s0, 0x1a00
	s_addc_u32 s1, s1, 0
	v_lshl_add_u64 v[0:1], s[0:1], 0, v[196:197]
	global_load_dword v25, v[0:1], off offset:1024
	global_load_dword v26, v[0:1], off offset:1536
	s_add_u32 s0, s0, 0x1a00
	s_addc_u32 s1, s1, 0
	v_lshl_add_u64 v[2:3], s[0:1], 0, v[196:197]
	global_load_dword v23, v[2:3], off offset:1024
	global_load_dword v24, v[2:3], off offset:1536
.Lkn3_skip_237:
	s_add_i32 s0, s24, s57
	s_add_i32 s0, s0, 0xfff80020
	s_ashr_i32 s4, s0, 2
	s_ashr_i32 s5, s4, 31
	s_lshl_b64 s[30:31], s[4:5], 8
	v_lshl_add_u64 v[200:201], v[190:191], 0, s[30:31]
	v_lshl_add_u64 v[202:203], v[192:193], 0, s[30:31]
	s_waitcnt vmcnt(12)
	v_lshlrev_b32_e32 v220, 16, v21
	v_and_b32_e32 v221, 0xffff0000, v21
	v_lshlrev_b32_e32 v228, 16, v22
	v_and_b32_e32 v229, 0xffff0000, v22
	v_lshlrev_b32_e32 v236, 16, v19
	v_and_b32_e32 v237, 0xffff0000, v19
	v_lshlrev_b32_e32 v244, 16, v20
	v_and_b32_e32 v245, 0xffff0000, v20
	v_mul_f32_e32 v224, v220, v220
	v_mul_f32_e32 v225, v221, v221
	v_mul_f32_e32 v232, v228, v228
	v_mul_f32_e32 v233, v229, v229
	v_mul_f32_e32 v240, v236, v236
	v_mul_f32_e32 v241, v237, v237
	v_mul_f32_e32 v248, v244, v244
	v_mul_f32_e32 v249, v245, v245
	v_fma_f32 v222, v220, v220, v225
	v_fma_f32 v223, v221, v221, v224
	v_fma_f32 v230, v228, v228, v233
	v_fma_f32 v231, v229, v229, v232
	v_fma_f32 v238, v236, v236, v241
	v_fma_f32 v239, v237, v237, v240
	v_fma_f32 v246, v244, v244, v249
	v_fma_f32 v247, v245, v245, v248
	v_add_f32_dpp v222, v222, v222 quad_perm:[1,0,3,2] row_mask:0xf bank_mask:0xf
	v_add_f32_dpp v223, v223, v223 quad_perm:[1,0,3,2] row_mask:0xf bank_mask:0xf
	v_add_f32_dpp v230, v230, v230 quad_perm:[1,0,3,2] row_mask:0xf bank_mask:0xf
	v_add_f32_dpp v231, v231, v231 quad_perm:[1,0,3,2] row_mask:0xf bank_mask:0xf
	v_add_f32_dpp v238, v238, v238 quad_perm:[1,0,3,2] row_mask:0xf bank_mask:0xf
	v_add_f32_dpp v239, v239, v239 quad_perm:[1,0,3,2] row_mask:0xf bank_mask:0xf
	v_add_f32_dpp v246, v246, v246 quad_perm:[1,0,3,2] row_mask:0xf bank_mask:0xf
	v_add_f32_dpp v247, v247, v247 quad_perm:[1,0,3,2] row_mask:0xf bank_mask:0xf
	v_add_f32_dpp v222, v222, v222 quad_perm:[2,3,0,1] row_mask:0xf bank_mask:0xf
	v_add_f32_dpp v223, v223, v223 quad_perm:[2,3,0,1] row_mask:0xf bank_mask:0xf
	v_add_f32_dpp v230, v230, v230 quad_perm:[2,3,0,1] row_mask:0xf bank_mask:0xf
	v_add_f32_dpp v231, v231, v231 quad_perm:[2,3,0,1] row_mask:0xf bank_mask:0xf
	v_add_f32_dpp v238, v238, v238 quad_perm:[2,3,0,1] row_mask:0xf bank_mask:0xf
	v_add_f32_dpp v239, v239, v239 quad_perm:[2,3,0,1] row_mask:0xf bank_mask:0xf
	v_add_f32_dpp v246, v246, v246 quad_perm:[2,3,0,1] row_mask:0xf bank_mask:0xf
	v_add_f32_dpp v247, v247, v247 quad_perm:[2,3,0,1] row_mask:0xf bank_mask:0xf
	ds_bpermute_b32 v224, v11, v222
	ds_bpermute_b32 v225, v11, v223
	ds_bpermute_b32 v232, v11, v230
	ds_bpermute_b32 v233, v11, v231
	ds_bpermute_b32 v240, v11, v238
	ds_bpermute_b32 v241, v11, v239
	ds_bpermute_b32 v248, v11, v246
	ds_bpermute_b32 v249, v11, v247
	s_waitcnt lgkmcnt(0)
; __device__ __forceinline__ float bf2f(unsigned short u) { return __uint_as_float((unsigned)u << 16); }
; __device__ __forceinline__ unsigned f2bf(float f) { unsigned u = __float_as_uint(f); return (u + 0x7fffu + ((u >> 16) & 1u)) >> 16; }
; __device__ __forceinline__ void knorm_item(const KArgs& a, int l, int item, int wave, int lane) {
;     ...
;         for (int i = 0; i < 16; ++i) { const int task = item * 1024 + wave * 128 + r0 + i, row = task >> 2, which = (task >> 1) & 1, g = task & 1;
;             v[i] = bf2f(Z[(size_t)row * ZW + (which ? ZC_KW : ZC_KS) + g * 64 + lane]); }
; #pragma unroll
;         for (int i = 0; i < 16; ++i) { const int task = item * 1024 + wave * 128 + r0 + i, row = task >> 2, which = (task >> 1) & 1, g = task & 1;
;             const float rstd = rsqrtf(wave_sum(v[i] * v[i]) * (1.f / 64.f) + EPS);
;             bf16_t* dst = (bf16_t*)(a.ws + (which ? WS_KWN : WS_KSN));
;             dst[(size_t)row * 128 + g * 64 + lane] = (bf16_t)f2bf(v[i] * rstd * kg); }
	v_add_f32_e32 v222, v222, v224
	v_add_f32_e32 v223, v223, v225
	v_add_f32_e32 v230, v230, v232
	v_add_f32_e32 v231, v231, v233
	v_add_f32_e32 v238, v238, v240
	v_add_f32_e32 v239, v239, v241
	v_add_f32_e32 v246, v246, v248
	v_add_f32_e32 v247, v247, v249
	v_add_f32_dpp v222, v222, v222 row_ror:8 row_mask:0xf bank_mask:0xf
	v_add_f32_dpp v223, v223, v223 row_ror:8 row_mask:0xf bank_mask:0xf
	v_add_f32_dpp v230, v230, v230 row_ror:8 row_mask:0xf bank_mask:0xf
	v_add_f32_dpp v231, v231, v231 row_ror:8 row_mask:0xf bank_mask:0xf
	v_add_f32_dpp v238, v238, v238 row_ror:8 row_mask:0xf bank_mask:0xf
	v_add_f32_dpp v239, v239, v239 row_ror:8 row_mask:0xf bank_mask:0xf
	v_add_f32_dpp v246, v246, v246 row_ror:8 row_mask:0xf bank_mask:0xf
	v_add_f32_dpp v247, v247, v247 row_ror:8 row_mask:0xf bank_mask:0xf
	ds_bpermute_b32 v224, v13, v222
	ds_bpermute_b32 v225, v13, v223
	ds_bpermute_b32 v232, v13, v230
	ds_bpermute_b32 v233, v13, v231
	ds_bpermute_b32 v240, v13, v238
	ds_bpermute_b32 v241, v13, v239
	ds_bpermute_b32 v248, v13, v246
	ds_bpermute_b32 v249, v13, v247
	s_waitcnt lgkmcnt(0)
	v_add_f32_e32 v222, v222, v224
	v_add_f32_e32 v223, v223, v225
	v_add_f32_e32 v230, v230, v232
	v_add_f32_e32 v231, v231, v233
	v_add_f32_e32 v238, v238, v240
	v_add_f32_e32 v239, v239, v241
	v_add_f32_e32 v246, v246, v248
	v_add_f32_e32 v247, v247, v249
	v_fma_f32 v222, v222, s22, v195
	v_fma_f32 v223, v223, s22, v195
	v_fma_f32 v230, v230, s22, v195
	v_fma_f32 v231, v231, s22, v195
	v_fma_f32 v238, v238, s22, v195
	v_fma_f32 v239, v239, s22, v195
	v_fma_f32 v246, v246, s22, v195
	v_fma_f32 v247, v247, s22, v195
	v_mul_f32_e32 v226, 0x4b800000, v222
	    v_mul_f32_e32 v227, 0x4b800000, v223
	    v_cmp_gt_f32_e64 s[4:5], s48, v222
	    v_cmp_gt_f32_e32 vcc, s48, v223
	    s_nop 1
	    v_cndmask_b32_e64 v222, v222, v226, s[4:5]
	    v_cndmask_b32_e32 v223, v223, v227, vcc
	    v_rsq_f32_e32 v222, v222
	    v_rsq_f32_e32 v223, v223
	    s_nop 0
	    v_mul_f32_e32 v226, 0x45800000, v222
	    v_mul_f32_e32 v227, 0x45800000, v223
	    v_cndmask_b32_e64 v222, v222, v226, s[4:5]
	    v_cndmask_b32_e32 v223, v223, v227, vcc
	    v_mul_f32_e32 v220, v222, v220
	    v_mul_f32_e32 v221, v223, v221
	    v_mul_f32_e32 v220, v184, v220
	    v_mul_f32_e32 v221, v185, v221
	    v_bfe_u32 v226, v220, 16, 1
	    v_bfe_u32 v227, v221, 16, 1
	    v_add3_u32 v220, v220, v226, s49
	    v_add3_u32 v221, v221, v227, s49
	    v_perm_b32 v21, v221, v220, v194
	    global_store_dword v[200:201], v21, off
	v_mul_f32_e32 v234, 0x4b800000, v230
	    v_mul_f32_e32 v235, 0x4b800000, v231
	    v_cmp_gt_f32_e64 s[4:5], s48, v230
	    v_cmp_gt_f32_e32 vcc, s48, v231
	    s_nop 1
	    v_cndmask_b32_e64 v230, v230, v234, s[4:5]
	    v_cndmask_b32_e32 v231, v231, v235, vcc
	    v_rsq_f32_e32 v230, v230
	    v_rsq_f32_e32 v231, v231
	    s_nop 0
	    v_mul_f32_e32 v234, 0x45800000, v230
	    v_mul_f32_e32 v235, 0x45800000, v231
	    v_cndmask_b32_e64 v230, v230, v234, s[4:5]
	    v_cndmask_b32_e32 v231, v231, v235, vcc
	    v_mul_f32_e32 v228, v230, v228
	    v_mul_f32_e32 v229, v231, v229
	    v_mul_f32_e32 v228, v184, v228
	    v_mul_f32_e32 v229, v185, v229
	    v_bfe_u32 v234, v228, 16, 1
	    v_bfe_u32 v235, v229, 16, 1
	    v_add3_u32 v228, v228, v234, s49
	    v_add3_u32 v229, v229, v235, s49
	    v_perm_b32 v22, v229, v228, v194
	    global_store_dword v[202:203], v22, off
	v_mul_f32_e32 v242, 0x4b800000, v238
	    v_mul_f32_e32 v243, 0x4b800000, v239
	    v_cmp_gt_f32_e64 s[4:5], s48, v238
	    v_cmp_gt_f32_e32 vcc, s48, v239
	    s_nop 1
	    v_cndmask_b32_e64 v238, v238, v242, s[4:5]
	    v_cndmask_b32_e32 v239, v239, v243, vcc
	    v_rsq_f32_e32 v238, v238
	    v_rsq_f32_e32 v239, v239
	    s_nop 0
	    v_mul_f32_e32 v242, 0x45800000, v238
	    v_mul_f32_e32 v243, 0x45800000, v239
	    v_cndmask_b32_e64 v238, v238, v242, s[4:5]
	    v_cndmask_b32_e32 v239, v239, v243, vcc
	    v_mul_f32_e32 v236, v238, v236
	    v_mul_f32_e32 v237, v239, v237
	    v_mul_f32_e32 v236, v184, v236
	    v_mul_f32_e32 v237, v185, v237
	    v_bfe_u32 v242, v236, 16, 1
	    v_bfe_u32 v243, v237, 16, 1
	    v_add3_u32 v236, v236, v242, s49
	    v_add3_u32 v237, v237, v243, s49
	    v_perm_b32 v19, v237, v236, v194
	    global_store_dword v[200:201], v19, off offset:256
	v_mul_f32_e32 v250, 0x4b800000, v246
	    v_mul_f32_e32 v251, 0x4b800000, v247
	    v_cmp_gt_f32_e64 s[4:5], s48, v246
	    v_cmp_gt_f32_e32 vcc, s48, v247
	    s_nop 1
	    v_cndmask_b32_e64 v246, v246, v250, s[4:5]
	    v_cndmask_b32_e32 v247, v247, v251, vcc
	    v_rsq_f32_e32 v246, v246
	    v_rsq_f32_e32 v247, v247
	    s_nop 0
	    v_mul_f32_e32 v250, 0x45800000, v246
	    v_mul_f32_e32 v251, 0x45800000, v247
	    v_cndmask_b32_e64 v246, v246, v250, s[4:5]
	    v_cndmask_b32_e32 v247, v247, v251, vcc
	    v_mul_f32_e32 v244, v246, v244
	    v_mul_f32_e32 v245, v247, v245
	    v_mul_f32_e32 v244, v184, v244
	    v_mul_f32_e32 v245, v185, v245
	    v_bfe_u32 v250, v244, 16, 1
	    v_bfe_u32 v251, v245, 16, 1
	    v_add3_u32 v244, v244, v250, s49
	    v_add3_u32 v245, v245, v251, s49
	    v_perm_b32 v20, v245, v244, v194
	    global_store_dword v[202:203], v20, off offset:256
	s_waitcnt vmcnt(12)
; __device__ __forceinline__ float bf2f(unsigned short u) { return __uint_as_float((unsigned)u << 16); }
; __device__ __forceinline__ void knorm_item(const KArgs& a, int l, int item, int wave, int lane) {
;     ...
;         for (int i = 0; i < 16; ++i) { const int task = item * 1024 + wave * 128 + r0 + i, row = task >> 2, which = (task >> 1) & 1, g = task & 1;
;             v[i] = bf2f(Z[(size_t)row * ZW + (which ? ZC_KW : ZC_KS) + g * 64 + lane]); }
; #pragma unroll
;         for (int i = 0; i < 16; ++i) { const int task = item * 1024 + wave * 128 + r0 + i, row = task >> 2, which = (task >> 1) & 1, g = task & 1;
;             const float rstd = rsqrtf(wave_sum(v[i] * v[i]) * (1.f / 64.f) + EPS);
	v_lshlrev_b32_e32 v220, 16, v17
	v_and_b32_e32 v221, 0xffff0000, v17
	v_lshlrev_b32_e32 v228, 16, v18
	v_and_b32_e32 v229, 0xffff0000, v18
	v_lshlrev_b32_e32 v236, 16, v15
	v_and_b32_e32 v237, 0xffff0000, v15
	v_lshlrev_b32_e32 v244, 16, v16
	v_and_b32_e32 v245, 0xffff0000, v16
	v_mul_f32_e32 v224, v220, v220
	v_mul_f32_e32 v225, v221, v221
	v_mul_f32_e32 v232, v228, v228
	v_mul_f32_e32 v233, v229, v229
	v_mul_f32_e32 v240, v236, v236
	v_mul_f32_e32 v241, v237, v237
	v_mul_f32_e32 v248, v244, v244
	v_mul_f32_e32 v249, v245, v245
	v_fma_f32 v222, v220, v220, v225
	v_fma_f32 v223, v221, v221, v224
	v_fma_f32 v230, v228, v228, v233
	v_fma_f32 v231, v229, v229, v232
	v_fma_f32 v238, v236, v236, v241
	v_fma_f32 v239, v237, v237, v240
	v_fma_f32 v246, v244, v244, v249
	v_fma_f32 v247, v245, v245, v248
	v_add_f32_dpp v222, v222, v222 quad_perm:[1,0,3,2] row_mask:0xf bank_mask:0xf
	v_add_f32_dpp v223, v223, v223 quad_perm:[1,0,3,2] row_mask:0xf bank_mask:0xf
	v_add_f32_dpp v230, v230, v230 quad_perm:[1,0,3,2] row_mask:0xf bank_mask:0xf
	v_add_f32_dpp v231, v231, v231 quad_perm:[1,0,3,2] row_mask:0xf bank_mask:0xf
	v_add_f32_dpp v238, v238, v238 quad_perm:[1,0,3,2] row_mask:0xf bank_mask:0xf
	v_add_f32_dpp v239, v239, v239 quad_perm:[1,0,3,2] row_mask:0xf bank_mask:0xf
	v_add_f32_dpp v246, v246, v246 quad_perm:[1,0,3,2] row_mask:0xf bank_mask:0xf
	v_add_f32_dpp v247, v247, v247 quad_perm:[1,0,3,2] row_mask:0xf bank_mask:0xf
	v_add_f32_dpp v222, v222, v222 quad_perm:[2,3,0,1] row_mask:0xf bank_mask:0xf
	v_add_f32_dpp v223, v223, v223 quad_perm:[2,3,0,1] row_mask:0xf bank_mask:0xf
	v_add_f32_dpp v230, v230, v230 quad_perm:[2,3,0,1] row_mask:0xf bank_mask:0xf
	v_add_f32_dpp v231, v231, v231 quad_perm:[2,3,0,1] row_mask:0xf bank_mask:0xf
	v_add_f32_dpp v238, v238, v238 quad_perm:[2,3,0,1] row_mask:0xf bank_mask:0xf
	v_add_f32_dpp v239, v239, v239 quad_perm:[2,3,0,1] row_mask:0xf bank_mask:0xf
	v_add_f32_dpp v246, v246, v246 quad_perm:[2,3,0,1] row_mask:0xf bank_mask:0xf
	v_add_f32_dpp v247, v247, v247 quad_perm:[2,3,0,1] row_mask:0xf bank_mask:0xf
	ds_bpermute_b32 v224, v11, v222
	ds_bpermute_b32 v225, v11, v223
	ds_bpermute_b32 v232, v11, v230
	ds_bpermute_b32 v233, v11, v231
	ds_bpermute_b32 v240, v11, v238
	ds_bpermute_b32 v241, v11, v239
	ds_bpermute_b32 v248, v11, v246
	ds_bpermute_b32 v249, v11, v247
	s_waitcnt lgkmcnt(0)
	v_add_f32_e32 v222, v222, v224
	v_add_f32_e32 v223, v223, v225
	v_add_f32_e32 v230, v230, v232
	v_add_f32_e32 v231, v231, v233
	v_add_f32_e32 v238, v238, v240
	v_add_f32_e32 v239, v239, v241
	v_add_f32_e32 v246, v246, v248
	v_add_f32_e32 v247, v247, v249
	v_add_f32_dpp v222, v222, v222 row_ror:8 row_mask:0xf bank_mask:0xf
	v_add_f32_dpp v223, v223, v223 row_ror:8 row_mask:0xf bank_mask:0xf
	v_add_f32_dpp v230, v230, v230 row_ror:8 row_mask:0xf bank_mask:0xf
	v_add_f32_dpp v231, v231, v231 row_ror:8 row_mask:0xf bank_mask:0xf
	v_add_f32_dpp v238, v238, v238 row_ror:8 row_mask:0xf bank_mask:0xf
	v_add_f32_dpp v239, v239, v239 row_ror:8 row_mask:0xf bank_mask:0xf
	v_add_f32_dpp v246, v246, v246 row_ror:8 row_mask:0xf bank_mask:0xf
	v_add_f32_dpp v247, v247, v247 row_ror:8 row_mask:0xf bank_mask:0xf
	ds_bpermute_b32 v224, v13, v222
	ds_bpermute_b32 v225, v13, v223
	ds_bpermute_b32 v232, v13, v230
	ds_bpermute_b32 v233, v13, v231
	ds_bpermute_b32 v240, v13, v238
	ds_bpermute_b32 v241, v13, v239
	ds_bpermute_b32 v248, v13, v246
	ds_bpermute_b32 v249, v13, v247
	s_waitcnt lgkmcnt(0)
; __device__ __forceinline__ unsigned f2bf(float f) { unsigned u = __float_as_uint(f); return (u + 0x7fffu + ((u >> 16) & 1u)) >> 16; }
; __device__ __forceinline__ void knorm_item(const KArgs& a, int l, int item, int wave, int lane) {
;     ...
;     for (int r0 = 0; r0 < 128; r0 += 16) {
;     ...
;             const float rstd = rsqrtf(wave_sum(v[i] * v[i]) * (1.f / 64.f) + EPS);
;             bf16_t* dst = (bf16_t*)(a.ws + (which ? WS_KWN : WS_KSN));
;             dst[(size_t)row * 128 + g * 64 + lane] = (bf16_t)f2bf(v[i] * rstd * kg); }
	v_add_f32_e32 v222, v222, v224
	v_add_f32_e32 v223, v223, v225
	v_add_f32_e32 v230, v230, v232
	v_add_f32_e32 v231, v231, v233
	v_add_f32_e32 v238, v238, v240
	v_add_f32_e32 v239, v239, v241
	v_add_f32_e32 v246, v246, v248
	v_add_f32_e32 v247, v247, v249
	v_fma_f32 v222, v222, s22, v195
	v_fma_f32 v223, v223, s22, v195
	v_fma_f32 v230, v230, s22, v195
	v_fma_f32 v231, v231, s22, v195
	v_fma_f32 v238, v238, s22, v195
	v_fma_f32 v239, v239, s22, v195
	v_fma_f32 v246, v246, s22, v195
	v_fma_f32 v247, v247, s22, v195
	v_mul_f32_e32 v226, 0x4b800000, v222
	    v_mul_f32_e32 v227, 0x4b800000, v223
	    v_cmp_gt_f32_e64 s[4:5], s48, v222
	    v_cmp_gt_f32_e32 vcc, s48, v223
	    s_nop 1
	    v_cndmask_b32_e64 v222, v222, v226, s[4:5]
	    v_cndmask_b32_e32 v223, v223, v227, vcc
	    v_rsq_f32_e32 v222, v222
	    v_rsq_f32_e32 v223, v223
	    s_nop 0
	    v_mul_f32_e32 v226, 0x45800000, v222
	    v_mul_f32_e32 v227, 0x45800000, v223
	    v_cndmask_b32_e64 v222, v222, v226, s[4:5]
	    v_cndmask_b32_e32 v223, v223, v227, vcc
	    v_mul_f32_e32 v220, v222, v220
	    v_mul_f32_e32 v221, v223, v221
	    v_mul_f32_e32 v220, v184, v220
	    v_mul_f32_e32 v221, v185, v221
	    v_bfe_u32 v226, v220, 16, 1
	    v_bfe_u32 v227, v221, 16, 1
	    v_add3_u32 v220, v220, v226, s49
	    v_add3_u32 v221, v221, v227, s49
	    v_perm_b32 v17, v221, v220, v194
	    global_store_dword v[200:201], v17, off offset:512
	v_mul_f32_e32 v234, 0x4b800000, v230
	    v_mul_f32_e32 v235, 0x4b800000, v231
	    v_cmp_gt_f32_e64 s[4:5], s48, v230
	    v_cmp_gt_f32_e32 vcc, s48, v231
	    s_nop 1
	    v_cndmask_b32_e64 v230, v230, v234, s[4:5]
	    v_cndmask_b32_e32 v231, v231, v235, vcc
	    v_rsq_f32_e32 v230, v230
	    v_rsq_f32_e32 v231, v231
	    s_nop 0
	    v_mul_f32_e32 v234, 0x45800000, v230
	    v_mul_f32_e32 v235, 0x45800000, v231
	    v_cndmask_b32_e64 v230, v230, v234, s[4:5]
	    v_cndmask_b32_e32 v231, v231, v235, vcc
	    v_mul_f32_e32 v228, v230, v228
	    v_mul_f32_e32 v229, v231, v229
	    v_mul_f32_e32 v228, v184, v228
	    v_mul_f32_e32 v229, v185, v229
	    v_bfe_u32 v234, v228, 16, 1
	    v_bfe_u32 v235, v229, 16, 1
	    v_add3_u32 v228, v228, v234, s49
	    v_add3_u32 v229, v229, v235, s49
	    v_perm_b32 v18, v229, v228, v194
	    global_store_dword v[202:203], v18, off offset:512
	v_mul_f32_e32 v242, 0x4b800000, v238
	    v_mul_f32_e32 v243, 0x4b800000, v239
	    v_cmp_gt_f32_e64 s[4:5], s48, v238
	    v_cmp_gt_f32_e32 vcc, s48, v239
	    s_nop 1
	    v_cndmask_b32_e64 v238, v238, v242, s[4:5]
	    v_cndmask_b32_e32 v239, v239, v243, vcc
	    v_rsq_f32_e32 v238, v238
	    v_rsq_f32_e32 v239, v239
	    s_nop 0
	    v_mul_f32_e32 v242, 0x45800000, v238
	    v_mul_f32_e32 v243, 0x45800000, v239
	    v_cndmask_b32_e64 v238, v238, v242, s[4:5]
	    v_cndmask_b32_e32 v239, v239, v243, vcc
	    v_mul_f32_e32 v236, v238, v236
	    v_mul_f32_e32 v237, v239, v237
	    v_mul_f32_e32 v236, v184, v236
	    v_mul_f32_e32 v237, v185, v237
	    v_bfe_u32 v242, v236, 16, 1
	    v_bfe_u32 v243, v237, 16, 1
	    v_add3_u32 v236, v236, v242, s49
	    v_add3_u32 v237, v237, v243, s49
	    v_perm_b32 v15, v237, v236, v194
	    global_store_dword v[200:201], v15, off offset:768
	v_mul_f32_e32 v250, 0x4b800000, v246
	    v_mul_f32_e32 v251, 0x4b800000, v247
	    v_cmp_gt_f32_e64 s[4:5], s48, v246
	    v_cmp_gt_f32_e32 vcc, s48, v247
	    s_nop 1
	    v_cndmask_b32_e64 v246, v246, v250, s[4:5]
	    v_cndmask_b32_e32 v247, v247, v251, vcc
	    v_rsq_f32_e32 v246, v246
	    v_rsq_f32_e32 v247, v247
	    s_nop 0
	    v_mul_f32_e32 v250, 0x45800000, v246
	    v_mul_f32_e32 v251, 0x45800000, v247
	    v_cndmask_b32_e64 v246, v246, v250, s[4:5]
	    v_cndmask_b32_e32 v247, v247, v251, vcc
	    v_mul_f32_e32 v244, v246, v244
	    v_mul_f32_e32 v245, v247, v245
	    v_mul_f32_e32 v244, v184, v244
	    v_mul_f32_e32 v245, v185, v245
	    v_bfe_u32 v250, v244, 16, 1
	    v_bfe_u32 v251, v245, 16, 1
	    v_add3_u32 v244, v244, v250, s49
	    v_add3_u32 v245, v245, v251, s49
	    v_perm_b32 v16, v245, v244, v194
	    global_store_dword v[202:203], v16, off offset:768
	s_add_i32 s57, s57, 32
	s_cmpk_gt_u32 s57, 0x6f
	s_cbranch_scc0 .LBB0_237
	s_mov_b64 s[0:1], 0

; __device__ __forceinline__ float bf2f(unsigned short u) { return __uint_as_float((unsigned)u << 16); }
; __device__ __forceinline__ void knorm_item(const KArgs& a, int l, int item, int wave, int lane) {
;     const bf16_t* Z = (const bf16_t*)(a.ws + WS_Z);
;     const float kg = a.in[I_KN][l * 64 + lane];
;     for (int r0 = 0; r0 < 128; r0 += 16) {
;         float v[16];
; #pragma unroll
;         for (int i = 0; i < 16; ++i) { const int task = item * 1024 + wave * 128 + r0 + i, row = task >> 2, which = (task >> 1) & 1, g = task & 1;
;             v[i] = bf2f(Z[(size_t)row * ZW + (which ? ZC_KW : ZC_KS) + g * 64 + lane]); }
; __device__ __forceinline__ void phase_mix1(const KArgs& a, int l, LAS unsigned char* lds, int wave, int lane, int ci) {
;     ...
;     for (;;) {
;         __syncthreads();
;         if (threadIdx.x == 0) *slot = (int)atomicAdd(ctr, 1u);
;         __syncthreads();
;         int r = *slot;
;         if (r >= N_R0 + N_CMP + N_CONV + N_KN) break;
;         if (r < N_R0) { ret0_item(a, l, r, lds, wave, lane); continue; } r -= N_R0;
;         if (r < N_CMP) { cmp_mfma_item(a, l, r, lds, wave, lane); continue; } r -= N_CMP;
;         if (r < N_CONV) { conv_item(a, l, r); continue; } r -= N_CONV;
;         knorm_item(a, l, r, wave, lane);
.LBB0_1033:
	s_or_b64 exec, exec, s[0:1]
	s_waitcnt lgkmcnt(0)
	s_barrier
	ds_read_b32 v0, v120
	s_movk_i32 s0, 0x2ff
	s_waitcnt lgkmcnt(0)
	v_cmp_lt_i32_e32 vcc, s0, v0
	v_readfirstlane_b32 s33, v0
	s_mov_b64 s[0:1], -1
	s_cbranch_vccnz .LBB0_1028
	s_cmpk_gt_i32 s33, 0x7f
	s_cbranch_scc0 .LBB0_1063
	s_cmpk_gt_u32 s33, 0xff
	s_cbranch_scc0 .LBB0_1044
	s_cmpk_gt_u32 s33, 0x1ff
	s_cbranch_scc0 .LBB0_1040
	global_load_dword v8, v[66:67], off offset:256
	v_cmp_lt_i32_e32 vcc, v124, v123
	s_lshl_b32 s0, s33, 10
	s_add_i32 s30, s40, s0
	v_cndmask_b32_e32 v0, v122, v124, vcc
	v_cmp_lt_i32_e32 vcc, v125, v123
	v_lshlrev_b32_e32 v9, 2, v0
	s_mov_b32 s63, -16
	v_cndmask_b32_e32 v0, v122, v125, vcc
	v_cmp_lt_i32_e32 vcc, v126, v123
	v_lshlrev_b32_e32 v10, 2, v0
	s_nop 0
	v_cndmask_b32_e32 v0, v122, v126, vcc
	v_cmp_lt_i32_e32 vcc, v127, v123
	v_lshlrev_b32_e32 v11, 2, v0
	s_nop 0
	v_cndmask_b32_e32 v0, v122, v127, vcc
	v_cmp_lt_i32_e32 vcc, v128, v123
	v_lshlrev_b32_e32 v12, 2, v0
	s_nop 0
	v_cndmask_b32_e32 v0, v122, v128, vcc
	v_cmp_lt_i32_e32 vcc, v129, v123
	v_lshlrev_b32_e32 v13, 2, v0
	s_nop 0
	v_cndmask_b32_e32 v0, v122, v129, vcc
	v_lshlrev_b32_e32 v14, 2, v0
	v_mbcnt_lo_u32_b32 v186, -1, 0
	v_mbcnt_hi_u32_b32 v186, -1, v186
	v_and_b32_e32 v188, 31, v186
	v_lshlrev_b32_e32 v188, 3, v188
	v_lshlrev_b32_e32 v187, 2, v186
	v_sub_u32_e32 v188, v188, v187
	v_ashrrev_i32_e32 v189, 31, v188
	v_lshl_add_u64 v[188:189], v[66:67], 0, v[188:189]
	global_load_dwordx2 v[184:185], v[188:189], off offset:256
	v_lshlrev_b32_e32 v186, 1, v186
	v_mov_b32_e32 v187, 0
	v_lshl_add_u64 v[190:191], v[68:69], 0, v[186:187]
	v_lshl_add_u64 v[192:193], v[70:71], 0, v[186:187]
	v_mov_b32_e32 v194, 0x7060302
	v_mov_b32_e32 v195, s26
	v_lshl_add_u64 v[196:197], v[64:65], 0, v[186:187]
	v_mov_b32_e32 v198, s53
	v_mov_b32_e32 v199, 0
	v_lshl_add_u64 v[196:197], v[196:197], 0, v[198:199]
	s_add_i32 s0, s30, s63
	s_add_i32 s0, s0, 0xfff80010
	s_ashr_i32 s4, s0, 2
	s_ashr_i32 s5, s4, 31
	s_mul_i32 s0, s4, 0x1a00
	s_mul_hi_i32 s1, s4, 0x1a00
	s_add_u32 s0, s92, s0
	s_addc_u32 s1, s93, s1
	v_lshl_add_u64 v[0:1], s[0:1], 0, v[196:197]
	global_load_dword v4, v[0:1], off offset:1024
	global_load_dword v6, v[0:1], off offset:1536
	s_add_u32 s0, s0, 0x1a00
	s_addc_u32 s1, s1, 0
	v_lshl_add_u64 v[2:3], s[0:1], 0, v[196:197]
	global_load_dword v27, v[2:3], off offset:1024
	global_load_dword v28, v[2:3], off offset:1536
	s_add_u32 s0, s0, 0x1a00
	s_addc_u32 s1, s1, 0
	v_lshl_add_u64 v[0:1], s[0:1], 0, v[196:197]
	global_load_dword v25, v[0:1], off offset:1024
	global_load_dword v26, v[0:1], off offset:1536
	s_add_u32 s0, s0, 0x1a00
	s_addc_u32 s1, s1, 0
	v_lshl_add_u64 v[2:3], s[0:1], 0, v[196:197]
	global_load_dword v23, v[2:3], off offset:1024
	global_load_dword v24, v[2:3], off offset:1536
.LBB0_1038:
	s_add_i32 s0, s30, s63
	s_add_i32 s0, s0, 0xfff80020
	s_ashr_i32 s4, s0, 2
	s_ashr_i32 s5, s4, 31
	s_mul_i32 s0, s4, 0x1a00
	s_mul_hi_i32 s1, s4, 0x1a00
	s_add_u32 s0, s92, s0
	s_addc_u32 s1, s93, s1
	v_lshl_add_u64 v[0:1], s[0:1], 0, v[196:197]
	global_load_dword v21, v[0:1], off offset:1024
	global_load_dword v22, v[0:1], off offset:1536
	s_add_u32 s0, s0, 0x1a00
	s_addc_u32 s1, s1, 0
	v_lshl_add_u64 v[2:3], s[0:1], 0, v[196:197]
	global_load_dword v19, v[2:3], off offset:1024
	global_load_dword v20, v[2:3], off offset:1536
	s_add_u32 s0, s0, 0x1a00
	s_addc_u32 s1, s1, 0
	v_lshl_add_u64 v[0:1], s[0:1], 0, v[196:197]
	global_load_dword v17, v[0:1], off offset:1024
	global_load_dword v18, v[0:1], off offset:1536
	s_add_u32 s0, s0, 0x1a00
	s_addc_u32 s1, s1, 0
	v_lshl_add_u64 v[2:3], s[0:1], 0, v[196:197]
	global_load_dword v15, v[2:3], off offset:1024
	global_load_dword v16, v[2:3], off offset:1536
	s_add_i32 s0, s30, s63
	s_add_i32 s0, s0, 0xfff80010
	s_ashr_i32 s4, s0, 2
	s_ashr_i32 s5, s4, 31
	s_lshl_b64 s[38:39], s[4:5], 8
	v_lshl_add_u64 v[200:201], v[190:191], 0, s[38:39]
	v_lshl_add_u64 v[202:203], v[192:193], 0, s[38:39]
	s_waitcnt vmcnt(12)
	v_lshlrev_b32_e32 v220, 16, v4
	v_and_b32_e32 v221, 0xffff0000, v4
	v_lshlrev_b32_e32 v228, 16, v6
	v_and_b32_e32 v229, 0xffff0000, v6
	v_lshlrev_b32_e32 v236, 16, v27
	v_and_b32_e32 v237, 0xffff0000, v27
	v_lshlrev_b32_e32 v244, 16, v28
	v_and_b32_e32 v245, 0xffff0000, v28
	v_mul_f32_e32 v224, v220, v220
	v_mul_f32_e32 v225, v221, v221
	v_mul_f32_e32 v232, v228, v228
	v_mul_f32_e32 v233, v229, v229
	v_mul_f32_e32 v240, v236, v236
	v_mul_f32_e32 v241, v237, v237
	v_mul_f32_e32 v248, v244, v244
	v_mul_f32_e32 v249, v245, v245
	v_fma_f32 v222, v220, v220, v225
	v_fma_f32 v223, v221, v221, v224
	v_fma_f32 v230, v228, v228, v233
	v_fma_f32 v231, v229, v229, v232
	v_fma_f32 v238, v236, v236, v241
	v_fma_f32 v239, v237, v237, v240
	v_fma_f32 v246, v244, v244, v249
	v_fma_f32 v247, v245, v245, v248
	v_add_f32_dpp v222, v222, v222 quad_perm:[1,0,3,2] row_mask:0xf bank_mask:0xf
	v_add_f32_dpp v223, v223, v223 quad_perm:[1,0,3,2] row_mask:0xf bank_mask:0xf
	v_add_f32_dpp v230, v230, v230 quad_perm:[1,0,3,2] row_mask:0xf bank_mask:0xf
	v_add_f32_dpp v231, v231, v231 quad_perm:[1,0,3,2] row_mask:0xf bank_mask:0xf
	v_add_f32_dpp v238, v238, v238 quad_perm:[1,0,3,2] row_mask:0xf bank_mask:0xf
	v_add_f32_dpp v239, v239, v239 quad_perm:[1,0,3,2] row_mask:0xf bank_mask:0xf
	v_add_f32_dpp v246, v246, v246 quad_perm:[1,0,3,2] row_mask:0xf bank_mask:0xf
	v_add_f32_dpp v247, v247, v247 quad_perm:[1,0,3,2] row_mask:0xf bank_mask:0xf
	v_add_f32_dpp v222, v222, v222 quad_perm:[2,3,0,1] row_mask:0xf bank_mask:0xf
	v_add_f32_dpp v223, v223, v223 quad_perm:[2,3,0,1] row_mask:0xf bank_mask:0xf
	v_add_f32_dpp v230, v230, v230 quad_perm:[2,3,0,1] row_mask:0xf bank_mask:0xf
	v_add_f32_dpp v231, v231, v231 quad_perm:[2,3,0,1] row_mask:0xf bank_mask:0xf
	v_add_f32_dpp v238, v238, v238 quad_perm:[2,3,0,1] row_mask:0xf bank_mask:0xf
	v_add_f32_dpp v239, v239, v239 quad_perm:[2,3,0,1] row_mask:0xf bank_mask:0xf
	v_add_f32_dpp v246, v246, v246 quad_perm:[2,3,0,1] row_mask:0xf bank_mask:0xf
	v_add_f32_dpp v247, v247, v247 quad_perm:[2,3,0,1] row_mask:0xf bank_mask:0xf
	ds_bpermute_b32 v224, v11, v222
	ds_bpermute_b32 v225, v11, v223
	ds_bpermute_b32 v232, v11, v230
	ds_bpermute_b32 v233, v11, v231
	ds_bpermute_b32 v240, v11, v238
	ds_bpermute_b32 v241, v11, v239
	ds_bpermute_b32 v248, v11, v246
	ds_bpermute_b32 v249, v11, v247
	s_waitcnt lgkmcnt(0)
; __device__ __forceinline__ float bf2f(unsigned short u) { return __uint_as_float((unsigned)u << 16); }
; __device__ __forceinline__ unsigned f2bf(float f) { unsigned u = __float_as_uint(f); return (u + 0x7fffu + ((u >> 16) & 1u)) >> 16; }
; __device__ __forceinline__ void knorm_item(const KArgs& a, int l, int item, int wave, int lane) {
;     ...
;         for (int i = 0; i < 16; ++i) { const int task = item * 1024 + wave * 128 + r0 + i, row = task >> 2, which = (task >> 1) & 1, g = task & 1;
;             v[i] = bf2f(Z[(size_t)row * ZW + (which ? ZC_KW : ZC_KS) + g * 64 + lane]); }
; #pragma unroll
;         for (int i = 0; i < 16; ++i) { const int task = item * 1024 + wave * 128 + r0 + i, row = task >> 2, which = (task >> 1) & 1, g = task & 1;
;             const float rstd = rsqrtf(wave_sum(v[i] * v[i]) * (1.f / 64.f) + EPS);
;             bf16_t* dst = (bf16_t*)(a.ws + (which ? WS_KWN : WS_KSN));
;             dst[(size_t)row * 128 + g * 64 + lane] = (bf16_t)f2bf(v[i] * rstd * kg); }
	v_add_f32_e32 v222, v222, v224
	v_add_f32_e32 v223, v223, v225
	v_add_f32_e32 v230, v230, v232
	v_add_f32_e32 v231, v231, v233
	v_add_f32_e32 v238, v238, v240
	v_add_f32_e32 v239, v239, v241
	v_add_f32_e32 v246, v246, v248
	v_add_f32_e32 v247, v247, v249
	v_add_f32_dpp v222, v222, v222 row_ror:8 row_mask:0xf bank_mask:0xf
	v_add_f32_dpp v223, v223, v223 row_ror:8 row_mask:0xf bank_mask:0xf
	v_add_f32_dpp v230, v230, v230 row_ror:8 row_mask:0xf bank_mask:0xf
	v_add_f32_dpp v231, v231, v231 row_ror:8 row_mask:0xf bank_mask:0xf
	v_add_f32_dpp v238, v238, v238 row_ror:8 row_mask:0xf bank_mask:0xf
	v_add_f32_dpp v239, v239, v239 row_ror:8 row_mask:0xf bank_mask:0xf
	v_add_f32_dpp v246, v246, v246 row_ror:8 row_mask:0xf bank_mask:0xf
	v_add_f32_dpp v247, v247, v247 row_ror:8 row_mask:0xf bank_mask:0xf
	ds_bpermute_b32 v224, v13, v222
	ds_bpermute_b32 v225, v13, v223
	ds_bpermute_b32 v232, v13, v230
	ds_bpermute_b32 v233, v13, v231
	ds_bpermute_b32 v240, v13, v238
	ds_bpermute_b32 v241, v13, v239
	ds_bpermute_b32 v248, v13, v246
	ds_bpermute_b32 v249, v13, v247
	s_waitcnt lgkmcnt(0)
	v_add_f32_e32 v222, v222, v224
	v_add_f32_e32 v223, v223, v225
	v_add_f32_e32 v230, v230, v232
	v_add_f32_e32 v231, v231, v233
	v_add_f32_e32 v238, v238, v240
	v_add_f32_e32 v239, v239, v241
	v_add_f32_e32 v246, v246, v248
	v_add_f32_e32 v247, v247, v249
	v_fma_f32 v222, v222, s28, v195
	v_fma_f32 v223, v223, s28, v195
	v_fma_f32 v230, v230, s28, v195
	v_fma_f32 v231, v231, s28, v195
	v_fma_f32 v238, v238, s28, v195
	v_fma_f32 v239, v239, s28, v195
	v_fma_f32 v246, v246, s28, v195
	v_fma_f32 v247, v247, s28, v195
	v_mul_f32_e32 v226, 0x4b800000, v222
	    v_mul_f32_e32 v227, 0x4b800000, v223
	    v_cmp_gt_f32_e64 s[4:5], s54, v222
	    v_cmp_gt_f32_e32 vcc, s54, v223
	    s_nop 1
	    v_cndmask_b32_e64 v222, v222, v226, s[4:5]
	    v_cndmask_b32_e32 v223, v223, v227, vcc
	    v_rsq_f32_e32 v222, v222
	    v_rsq_f32_e32 v223, v223
	    s_nop 0
	    v_mul_f32_e32 v226, 0x45800000, v222
	    v_mul_f32_e32 v227, 0x45800000, v223
	    v_cndmask_b32_e64 v222, v222, v226, s[4:5]
	    v_cndmask_b32_e32 v223, v223, v227, vcc
	    v_mul_f32_e32 v220, v222, v220
	    v_mul_f32_e32 v221, v223, v221
	    v_mul_f32_e32 v220, v184, v220
	    v_mul_f32_e32 v221, v185, v221
	    v_bfe_u32 v226, v220, 16, 1
	    v_bfe_u32 v227, v221, 16, 1
	    v_add3_u32 v220, v220, v226, s55
	    v_add3_u32 v221, v221, v227, s55
	    v_perm_b32 v4, v221, v220, v194
	    global_store_dword v[200:201], v4, off
	v_mul_f32_e32 v234, 0x4b800000, v230
	    v_mul_f32_e32 v235, 0x4b800000, v231
	    v_cmp_gt_f32_e64 s[4:5], s54, v230
	    v_cmp_gt_f32_e32 vcc, s54, v231
	    s_nop 1
	    v_cndmask_b32_e64 v230, v230, v234, s[4:5]
	    v_cndmask_b32_e32 v231, v231, v235, vcc
	    v_rsq_f32_e32 v230, v230
	    v_rsq_f32_e32 v231, v231
	    s_nop 0
	    v_mul_f32_e32 v234, 0x45800000, v230
	    v_mul_f32_e32 v235, 0x45800000, v231
	    v_cndmask_b32_e64 v230, v230, v234, s[4:5]
	    v_cndmask_b32_e32 v231, v231, v235, vcc
	    v_mul_f32_e32 v228, v230, v228
	    v_mul_f32_e32 v229, v231, v229
	    v_mul_f32_e32 v228, v184, v228
	    v_mul_f32_e32 v229, v185, v229
	    v_bfe_u32 v234, v228, 16, 1
	    v_bfe_u32 v235, v229, 16, 1
	    v_add3_u32 v228, v228, v234, s55
	    v_add3_u32 v229, v229, v235, s55
	    v_perm_b32 v6, v229, v228, v194
	    global_store_dword v[202:203], v6, off
	v_mul_f32_e32 v242, 0x4b800000, v238
	    v_mul_f32_e32 v243, 0x4b800000, v239
	    v_cmp_gt_f32_e64 s[4:5], s54, v238
	    v_cmp_gt_f32_e32 vcc, s54, v239
	    s_nop 1
	    v_cndmask_b32_e64 v238, v238, v242, s[4:5]
	    v_cndmask_b32_e32 v239, v239, v243, vcc
	    v_rsq_f32_e32 v238, v238
	    v_rsq_f32_e32 v239, v239
	    s_nop 0
	    v_mul_f32_e32 v242, 0x45800000, v238
	    v_mul_f32_e32 v243, 0x45800000, v239
	    v_cndmask_b32_e64 v238, v238, v242, s[4:5]
	    v_cndmask_b32_e32 v239, v239, v243, vcc
	    v_mul_f32_e32 v236, v238, v236
	    v_mul_f32_e32 v237, v239, v237
	    v_mul_f32_e32 v236, v184, v236
	    v_mul_f32_e32 v237, v185, v237
	    v_bfe_u32 v242, v236, 16, 1
	    v_bfe_u32 v243, v237, 16, 1
	    v_add3_u32 v236, v236, v242, s55
	    v_add3_u32 v237, v237, v243, s55
	    v_perm_b32 v27, v237, v236, v194
	    global_store_dword v[200:201], v27, off offset:256
	v_mul_f32_e32 v250, 0x4b800000, v246
	    v_mul_f32_e32 v251, 0x4b800000, v247
	    v_cmp_gt_f32_e64 s[4:5], s54, v246
	    v_cmp_gt_f32_e32 vcc, s54, v247
	    s_nop 1
	    v_cndmask_b32_e64 v246, v246, v250, s[4:5]
	    v_cndmask_b32_e32 v247, v247, v251, vcc
	    v_rsq_f32_e32 v246, v246
	    v_rsq_f32_e32 v247, v247
	    s_nop 0
	    v_mul_f32_e32 v250, 0x45800000, v246
	    v_mul_f32_e32 v251, 0x45800000, v247
	    v_cndmask_b32_e64 v246, v246, v250, s[4:5]
	    v_cndmask_b32_e32 v247, v247, v251, vcc
	    v_mul_f32_e32 v244, v246, v244
	    v_mul_f32_e32 v245, v247, v245
	    v_mul_f32_e32 v244, v184, v244
	    v_mul_f32_e32 v245, v185, v245
	    v_bfe_u32 v250, v244, 16, 1
	    v_bfe_u32 v251, v245, 16, 1
	    v_add3_u32 v244, v244, v250, s55
	    v_add3_u32 v245, v245, v251, s55
	    v_perm_b32 v28, v245, v244, v194
	    global_store_dword v[202:203], v28, off offset:256
	s_waitcnt vmcnt(12)
; __device__ __forceinline__ float bf2f(unsigned short u) { return __uint_as_float((unsigned)u << 16); }
; __device__ __forceinline__ unsigned f2bf(float f) { unsigned u = __float_as_uint(f); return (u + 0x7fffu + ((u >> 16) & 1u)) >> 16; }
; __device__ __forceinline__ void knorm_item(const KArgs& a, int l, int item, int wave, int lane) {
;     ...
;         for (int i = 0; i < 16; ++i) { const int task = item * 1024 + wave * 128 + r0 + i, row = task >> 2, which = (task >> 1) & 1, g = task & 1;
;             v[i] = bf2f(Z[(size_t)row * ZW + (which ? ZC_KW : ZC_KS) + g * 64 + lane]); }
; #pragma unroll
;         for (int i = 0; i < 16; ++i) { const int task = item * 1024 + wave * 128 + r0 + i, row = task >> 2, which = (task >> 1) & 1, g = task & 1;
;             const float rstd = rsqrtf(wave_sum(v[i] * v[i]) * (1.f / 64.f) + EPS);
;             bf16_t* dst = (bf16_t*)(a.ws + (which ? WS_KWN : WS_KSN));
;             dst[(size_t)row * 128 + g * 64 + lane] = (bf16_t)f2bf(v[i] * rstd * kg); }
	v_lshlrev_b32_e32 v220, 16, v25
	v_and_b32_e32 v221, 0xffff0000, v25
	v_lshlrev_b32_e32 v228, 16, v26
	v_and_b32_e32 v229, 0xffff0000, v26
	v_lshlrev_b32_e32 v236, 16, v23
	v_and_b32_e32 v237, 0xffff0000, v23
	v_lshlrev_b32_e32 v244, 16, v24
	v_and_b32_e32 v245, 0xffff0000, v24
	v_mul_f32_e32 v224, v220, v220
	v_mul_f32_e32 v225, v221, v221
	v_mul_f32_e32 v232, v228, v228
	v_mul_f32_e32 v233, v229, v229
	v_mul_f32_e32 v240, v236, v236
	v_mul_f32_e32 v241, v237, v237
	v_mul_f32_e32 v248, v244, v244
	v_mul_f32_e32 v249, v245, v245
	v_fma_f32 v222, v220, v220, v225
	v_fma_f32 v223, v221, v221, v224
	v_fma_f32 v230, v228, v228, v233
	v_fma_f32 v231, v229, v229, v232
	v_fma_f32 v238, v236, v236, v241
	v_fma_f32 v239, v237, v237, v240
	v_fma_f32 v246, v244, v244, v249
	v_fma_f32 v247, v245, v245, v248
	v_add_f32_dpp v222, v222, v222 quad_perm:[1,0,3,2] row_mask:0xf bank_mask:0xf
	v_add_f32_dpp v223, v223, v223 quad_perm:[1,0,3,2] row_mask:0xf bank_mask:0xf
	v_add_f32_dpp v230, v230, v230 quad_perm:[1,0,3,2] row_mask:0xf bank_mask:0xf
	v_add_f32_dpp v231, v231, v231 quad_perm:[1,0,3,2] row_mask:0xf bank_mask:0xf
	v_add_f32_dpp v238, v238, v238 quad_perm:[1,0,3,2] row_mask:0xf bank_mask:0xf
	v_add_f32_dpp v239, v239, v239 quad_perm:[1,0,3,2] row_mask:0xf bank_mask:0xf
	v_add_f32_dpp v246, v246, v246 quad_perm:[1,0,3,2] row_mask:0xf bank_mask:0xf
	v_add_f32_dpp v247, v247, v247 quad_perm:[1,0,3,2] row_mask:0xf bank_mask:0xf
	v_add_f32_dpp v222, v222, v222 quad_perm:[2,3,0,1] row_mask:0xf bank_mask:0xf
	v_add_f32_dpp v223, v223, v223 quad_perm:[2,3,0,1] row_mask:0xf bank_mask:0xf
	v_add_f32_dpp v230, v230, v230 quad_perm:[2,3,0,1] row_mask:0xf bank_mask:0xf
	v_add_f32_dpp v231, v231, v231 quad_perm:[2,3,0,1] row_mask:0xf bank_mask:0xf
	v_add_f32_dpp v238, v238, v238 quad_perm:[2,3,0,1] row_mask:0xf bank_mask:0xf
	v_add_f32_dpp v239, v239, v239 quad_perm:[2,3,0,1] row_mask:0xf bank_mask:0xf
	v_add_f32_dpp v246, v246, v246 quad_perm:[2,3,0,1] row_mask:0xf bank_mask:0xf
	v_add_f32_dpp v247, v247, v247 quad_perm:[2,3,0,1] row_mask:0xf bank_mask:0xf
	ds_bpermute_b32 v224, v11, v222
	ds_bpermute_b32 v225, v11, v223
	ds_bpermute_b32 v232, v11, v230
	ds_bpermute_b32 v233, v11, v231
	ds_bpermute_b32 v240, v11, v238
	ds_bpermute_b32 v241, v11, v239
	ds_bpermute_b32 v248, v11, v246
	ds_bpermute_b32 v249, v11, v247
	s_waitcnt lgkmcnt(0)
	v_add_f32_e32 v222, v222, v224
	v_add_f32_e32 v223, v223, v225
	v_add_f32_e32 v230, v230, v232
	v_add_f32_e32 v231, v231, v233
	v_add_f32_e32 v238, v238, v240
	v_add_f32_e32 v239, v239, v241
	v_add_f32_e32 v246, v246, v248
	v_add_f32_e32 v247, v247, v249
	v_add_f32_dpp v222, v222, v222 row_ror:8 row_mask:0xf bank_mask:0xf
	v_add_f32_dpp v223, v223, v223 row_ror:8 row_mask:0xf bank_mask:0xf
	v_add_f32_dpp v230, v230, v230 row_ror:8 row_mask:0xf bank_mask:0xf
	v_add_f32_dpp v231, v231, v231 row_ror:8 row_mask:0xf bank_mask:0xf
	v_add_f32_dpp v238, v238, v238 row_ror:8 row_mask:0xf bank_mask:0xf
	v_add_f32_dpp v239, v239, v239 row_ror:8 row_mask:0xf bank_mask:0xf
	v_add_f32_dpp v246, v246, v246 row_ror:8 row_mask:0xf bank_mask:0xf
	v_add_f32_dpp v247, v247, v247 row_ror:8 row_mask:0xf bank_mask:0xf
	ds_bpermute_b32 v224, v13, v222
	ds_bpermute_b32 v225, v13, v223
	ds_bpermute_b32 v232, v13, v230
	ds_bpermute_b32 v233, v13, v231
	ds_bpermute_b32 v240, v13, v238
	ds_bpermute_b32 v241, v13, v239
	ds_bpermute_b32 v248, v13, v246
	ds_bpermute_b32 v249, v13, v247
	s_waitcnt lgkmcnt(0)
	v_add_f32_e32 v222, v222, v224
	v_add_f32_e32 v223, v223, v225
	v_add_f32_e32 v230, v230, v232
	v_add_f32_e32 v231, v231, v233
	v_add_f32_e32 v238, v238, v240
	v_add_f32_e32 v239, v239, v241
	v_add_f32_e32 v246, v246, v248
	v_add_f32_e32 v247, v247, v249
	v_fma_f32 v222, v222, s28, v195
	v_fma_f32 v223, v223, s28, v195
	v_fma_f32 v230, v230, s28, v195
	v_fma_f32 v231, v231, s28, v195
	v_fma_f32 v238, v238, s28, v195
	v_fma_f32 v239, v239, s28, v195
	v_fma_f32 v246, v246, s28, v195
	v_fma_f32 v247, v247, s28, v195
	v_mul_f32_e32 v226, 0x4b800000, v222
	    v_mul_f32_e32 v227, 0x4b800000, v223
	    v_cmp_gt_f32_e64 s[4:5], s54, v222
	    v_cmp_gt_f32_e32 vcc, s54, v223
	    s_nop 1
	    v_cndmask_b32_e64 v222, v222, v226, s[4:5]
	    v_cndmask_b32_e32 v223, v223, v227, vcc
	    v_rsq_f32_e32 v222, v222
	    v_rsq_f32_e32 v223, v223
	    s_nop 0
	    v_mul_f32_e32 v226, 0x45800000, v222
	    v_mul_f32_e32 v227, 0x45800000, v223
	    v_cndmask_b32_e64 v222, v222, v226, s[4:5]
	    v_cndmask_b32_e32 v223, v223, v227, vcc
	    v_mul_f32_e32 v220, v222, v220
	    v_mul_f32_e32 v221, v223, v221
	    v_mul_f32_e32 v220, v184, v220
	    v_mul_f32_e32 v221, v185, v221
	    v_bfe_u32 v226, v220, 16, 1
	    v_bfe_u32 v227, v221, 16, 1
	    v_add3_u32 v220, v220, v226, s55
	    v_add3_u32 v221, v221, v227, s55
	    v_perm_b32 v25, v221, v220, v194
	    global_store_dword v[200:201], v25, off offset:512
	v_mul_f32_e32 v234, 0x4b800000, v230
	    v_mul_f32_e32 v235, 0x4b800000, v231
	    v_cmp_gt_f32_e64 s[4:5], s54, v230
	    v_cmp_gt_f32_e32 vcc, s54, v231
	    s_nop 1
	    v_cndmask_b32_e64 v230, v230, v234, s[4:5]
	    v_cndmask_b32_e32 v231, v231, v235, vcc
	    v_rsq_f32_e32 v230, v230
	    v_rsq_f32_e32 v231, v231
	    s_nop 0
	    v_mul_f32_e32 v234, 0x45800000, v230
	    v_mul_f32_e32 v235, 0x45800000, v231
	    v_cndmask_b32_e64 v230, v230, v234, s[4:5]
	    v_cndmask_b32_e32 v231, v231, v235, vcc
	    v_mul_f32_e32 v228, v230, v228
	    v_mul_f32_e32 v229, v231, v229
	    v_mul_f32_e32 v228, v184, v228
	    v_mul_f32_e32 v229, v185, v229
	    v_bfe_u32 v234, v228, 16, 1
	    v_bfe_u32 v235, v229, 16, 1
	    v_add3_u32 v228, v228, v234, s55
; __device__ __forceinline__ float bf2f(unsigned short u) { return __uint_as_float((unsigned)u << 16); }
; __device__ __forceinline__ unsigned f2bf(float f) { unsigned u = __float_as_uint(f); return (u + 0x7fffu + ((u >> 16) & 1u)) >> 16; }
; __device__ __forceinline__ void knorm_item(const KArgs& a, int l, int item, int wave, int lane) {
;     ...
;     for (int r0 = 0; r0 < 128; r0 += 16) {
;         float v[16];
; #pragma unroll
;         for (int i = 0; i < 16; ++i) { const int task = item * 1024 + wave * 128 + r0 + i, row = task >> 2, which = (task >> 1) & 1, g = task & 1;
;             v[i] = bf2f(Z[(size_t)row * ZW + (which ? ZC_KW : ZC_KS) + g * 64 + lane]); }
;     ...
;             const float rstd = rsqrtf(wave_sum(v[i] * v[i]) * (1.f / 64.f) + EPS);
;             bf16_t* dst = (bf16_t*)(a.ws + (which ? WS_KWN : WS_KSN));
;             dst[(size_t)row * 128 + g * 64 + lane] = (bf16_t)f2bf(v[i] * rstd * kg); }
	    v_add3_u32 v229, v229, v235, s55
	    v_perm_b32 v26, v229, v228, v194
	    global_store_dword v[202:203], v26, off offset:512
	v_mul_f32_e32 v242, 0x4b800000, v238
	    v_mul_f32_e32 v243, 0x4b800000, v239
	    v_cmp_gt_f32_e64 s[4:5], s54, v238
	    v_cmp_gt_f32_e32 vcc, s54, v239
	    s_nop 1
	    v_cndmask_b32_e64 v238, v238, v242, s[4:5]
	    v_cndmask_b32_e32 v239, v239, v243, vcc
	    v_rsq_f32_e32 v238, v238
	    v_rsq_f32_e32 v239, v239
	    s_nop 0
	    v_mul_f32_e32 v242, 0x45800000, v238
	    v_mul_f32_e32 v243, 0x45800000, v239
	    v_cndmask_b32_e64 v238, v238, v242, s[4:5]
	    v_cndmask_b32_e32 v239, v239, v243, vcc
	    v_mul_f32_e32 v236, v238, v236
	    v_mul_f32_e32 v237, v239, v237
	    v_mul_f32_e32 v236, v184, v236
	    v_mul_f32_e32 v237, v185, v237
	    v_bfe_u32 v242, v236, 16, 1
	    v_bfe_u32 v243, v237, 16, 1
	    v_add3_u32 v236, v236, v242, s55
	    v_add3_u32 v237, v237, v243, s55
	    v_perm_b32 v23, v237, v236, v194
	    global_store_dword v[200:201], v23, off offset:768
	v_mul_f32_e32 v250, 0x4b800000, v246
	    v_mul_f32_e32 v251, 0x4b800000, v247
	    v_cmp_gt_f32_e64 s[4:5], s54, v246
	    v_cmp_gt_f32_e32 vcc, s54, v247
	    s_nop 1
	    v_cndmask_b32_e64 v246, v246, v250, s[4:5]
	    v_cndmask_b32_e32 v247, v247, v251, vcc
	    v_rsq_f32_e32 v246, v246
	    v_rsq_f32_e32 v247, v247
	    s_nop 0
	    v_mul_f32_e32 v250, 0x45800000, v246
	    v_mul_f32_e32 v251, 0x45800000, v247
	    v_cndmask_b32_e64 v246, v246, v250, s[4:5]
	    v_cndmask_b32_e32 v247, v247, v251, vcc
	    v_mul_f32_e32 v244, v246, v244
	    v_mul_f32_e32 v245, v247, v245
	    v_mul_f32_e32 v244, v184, v244
	    v_mul_f32_e32 v245, v185, v245
	    v_bfe_u32 v250, v244, 16, 1
	    v_bfe_u32 v251, v245, 16, 1
	    v_add3_u32 v244, v244, v250, s55
	    v_add3_u32 v245, v245, v251, s55
	    v_perm_b32 v24, v245, v244, v194
	    global_store_dword v[202:203], v24, off offset:768
	s_cmpk_gt_i32 s63, 64
	s_cbranch_scc1 .Lkn3_skip_1038
	s_add_i32 s0, s30, s63
	s_add_i32 s0, s0, 0xfff80030
	s_ashr_i32 s4, s0, 2
	s_ashr_i32 s5, s4, 31
	s_mul_i32 s0, s4, 0x1a00
	s_mul_hi_i32 s1, s4, 0x1a00
	s_add_u32 s0, s92, s0
	s_addc_u32 s1, s93, s1
	v_lshl_add_u64 v[0:1], s[0:1], 0, v[196:197]
	global_load_dword v4, v[0:1], off offset:1024
	global_load_dword v6, v[0:1], off offset:1536
	s_add_u32 s0, s0, 0x1a00
	s_addc_u32 s1, s1, 0
	v_lshl_add_u64 v[2:3], s[0:1], 0, v[196:197]
	global_load_dword v27, v[2:3], off offset:1024
	global_load_dword v28, v[2:3], off offset:1536
	s_add_u32 s0, s0, 0x1a00
	s_addc_u32 s1, s1, 0
	v_lshl_add_u64 v[0:1], s[0:1], 0, v[196:197]
	global_load_dword v25, v[0:1], off offset:1024
	global_load_dword v26, v[0:1], off offset:1536
	s_add_u32 s0, s0, 0x1a00
	s_addc_u32 s1, s1, 0
	v_lshl_add_u64 v[2:3], s[0:1], 0, v[196:197]
	global_load_dword v23, v[2:3], off offset:1024
	global_load_dword v24, v[2:3], off offset:1536
.Lkn3_skip_1038:
	s_add_i32 s0, s30, s63
	s_add_i32 s0, s0, 0xfff80020
	s_ashr_i32 s4, s0, 2
	s_ashr_i32 s5, s4, 31
	s_lshl_b64 s[38:39], s[4:5], 8
	v_lshl_add_u64 v[200:201], v[190:191], 0, s[38:39]
	v_lshl_add_u64 v[202:203], v[192:193], 0, s[38:39]
	s_waitcnt vmcnt(12)
	v_lshlrev_b32_e32 v220, 16, v21
	v_and_b32_e32 v221, 0xffff0000, v21
	v_lshlrev_b32_e32 v228, 16, v22
	v_and_b32_e32 v229, 0xffff0000, v22
	v_lshlrev_b32_e32 v236, 16, v19
	v_and_b32_e32 v237, 0xffff0000, v19
	v_lshlrev_b32_e32 v244, 16, v20
	v_and_b32_e32 v245, 0xffff0000, v20
	v_mul_f32_e32 v224, v220, v220
	v_mul_f32_e32 v225, v221, v221
	v_mul_f32_e32 v232, v228, v228
	v_mul_f32_e32 v233, v229, v229
	v_mul_f32_e32 v240, v236, v236
	v_mul_f32_e32 v241, v237, v237
	v_mul_f32_e32 v248, v244, v244
	v_mul_f32_e32 v249, v245, v245
	v_fma_f32 v222, v220, v220, v225
	v_fma_f32 v223, v221, v221, v224
	v_fma_f32 v230, v228, v228, v233
	v_fma_f32 v231, v229, v229, v232
	v_fma_f32 v238, v236, v236, v241
	v_fma_f32 v239, v237, v237, v240
	v_fma_f32 v246, v244, v244, v249
	v_fma_f32 v247, v245, v245, v248
	v_add_f32_dpp v222, v222, v222 quad_perm:[1,0,3,2] row_mask:0xf bank_mask:0xf
	v_add_f32_dpp v223, v223, v223 quad_perm:[1,0,3,2] row_mask:0xf bank_mask:0xf
	v_add_f32_dpp v230, v230, v230 quad_perm:[1,0,3,2] row_mask:0xf bank_mask:0xf
	v_add_f32_dpp v231, v231, v231 quad_perm:[1,0,3,2] row_mask:0xf bank_mask:0xf
	v_add_f32_dpp v238, v238, v238 quad_perm:[1,0,3,2] row_mask:0xf bank_mask:0xf
	v_add_f32_dpp v239, v239, v239 quad_perm:[1,0,3,2] row_mask:0xf bank_mask:0xf
	v_add_f32_dpp v246, v246, v246 quad_perm:[1,0,3,2] row_mask:0xf bank_mask:0xf
	v_add_f32_dpp v247, v247, v247 quad_perm:[1,0,3,2] row_mask:0xf bank_mask:0xf
	v_add_f32_dpp v222, v222, v222 quad_perm:[2,3,0,1] row_mask:0xf bank_mask:0xf
	v_add_f32_dpp v223, v223, v223 quad_perm:[2,3,0,1] row_mask:0xf bank_mask:0xf
	v_add_f32_dpp v230, v230, v230 quad_perm:[2,3,0,1] row_mask:0xf bank_mask:0xf
	v_add_f32_dpp v231, v231, v231 quad_perm:[2,3,0,1] row_mask:0xf bank_mask:0xf
	v_add_f32_dpp v238, v238, v238 quad_perm:[2,3,0,1] row_mask:0xf bank_mask:0xf
	v_add_f32_dpp v239, v239, v239 quad_perm:[2,3,0,1] row_mask:0xf bank_mask:0xf
	v_add_f32_dpp v246, v246, v246 quad_perm:[2,3,0,1] row_mask:0xf bank_mask:0xf
	v_add_f32_dpp v247, v247, v247 quad_perm:[2,3,0,1] row_mask:0xf bank_mask:0xf
	ds_bpermute_b32 v224, v11, v222
	ds_bpermute_b32 v225, v11, v223
	ds_bpermute_b32 v232, v11, v230
	ds_bpermute_b32 v233, v11, v231
	ds_bpermute_b32 v240, v11, v238
	ds_bpermute_b32 v241, v11, v239
	ds_bpermute_b32 v248, v11, v246
	ds_bpermute_b32 v249, v11, v247
	s_waitcnt lgkmcnt(0)
; __device__ __forceinline__ float bf2f(unsigned short u) { return __uint_as_float((unsigned)u << 16); }
; __device__ __forceinline__ unsigned f2bf(float f) { unsigned u = __float_as_uint(f); return (u + 0x7fffu + ((u >> 16) & 1u)) >> 16; }
; __device__ __forceinline__ void knorm_item(const KArgs& a, int l, int item, int wave, int lane) {
;     ...
;         for (int i = 0; i < 16; ++i) { const int task = item * 1024 + wave * 128 + r0 + i, row = task >> 2, which = (task >> 1) & 1, g = task & 1;
;             v[i] = bf2f(Z[(size_t)row * ZW + (which ? ZC_KW : ZC_KS) + g * 64 + lane]); }
; #pragma unroll
;         for (int i = 0; i < 16; ++i) { const int task = item * 1024 + wave * 128 + r0 + i, row = task >> 2, which = (task >> 1) & 1, g = task & 1;
;             const float rstd = rsqrtf(wave_sum(v[i] * v[i]) * (1.f / 64.f) + EPS);
;             bf16_t* dst = (bf16_t*)(a.ws + (which ? WS_KWN : WS_KSN));
;             dst[(size_t)row * 128 + g * 64 + lane] = (bf16_t)f2bf(v[i] * rstd * kg); }
	v_add_f32_e32 v222, v222, v224
	v_add_f32_e32 v223, v223, v225
	v_add_f32_e32 v230, v230, v232
	v_add_f32_e32 v231, v231, v233
	v_add_f32_e32 v238, v238, v240
	v_add_f32_e32 v239, v239, v241
	v_add_f32_e32 v246, v246, v248
	v_add_f32_e32 v247, v247, v249
	v_add_f32_dpp v222, v222, v222 row_ror:8 row_mask:0xf bank_mask:0xf
	v_add_f32_dpp v223, v223, v223 row_ror:8 row_mask:0xf bank_mask:0xf
	v_add_f32_dpp v230, v230, v230 row_ror:8 row_mask:0xf bank_mask:0xf
	v_add_f32_dpp v231, v231, v231 row_ror:8 row_mask:0xf bank_mask:0xf
	v_add_f32_dpp v238, v238, v238 row_ror:8 row_mask:0xf bank_mask:0xf
	v_add_f32_dpp v239, v239, v239 row_ror:8 row_mask:0xf bank_mask:0xf
	v_add_f32_dpp v246, v246, v246 row_ror:8 row_mask:0xf bank_mask:0xf
	v_add_f32_dpp v247, v247, v247 row_ror:8 row_mask:0xf bank_mask:0xf
	ds_bpermute_b32 v224, v13, v222
	ds_bpermute_b32 v225, v13, v223
	ds_bpermute_b32 v232, v13, v230
	ds_bpermute_b32 v233, v13, v231
	ds_bpermute_b32 v240, v13, v238
	ds_bpermute_b32 v241, v13, v239
	ds_bpermute_b32 v248, v13, v246
	ds_bpermute_b32 v249, v13, v247
	s_waitcnt lgkmcnt(0)
	v_add_f32_e32 v222, v222, v224
	v_add_f32_e32 v223, v223, v225
	v_add_f32_e32 v230, v230, v232
	v_add_f32_e32 v231, v231, v233
	v_add_f32_e32 v238, v238, v240
	v_add_f32_e32 v239, v239, v241
	v_add_f32_e32 v246, v246, v248
	v_add_f32_e32 v247, v247, v249
	v_fma_f32 v222, v222, s28, v195
	v_fma_f32 v223, v223, s28, v195
	v_fma_f32 v230, v230, s28, v195
	v_fma_f32 v231, v231, s28, v195
	v_fma_f32 v238, v238, s28, v195
	v_fma_f32 v239, v239, s28, v195
	v_fma_f32 v246, v246, s28, v195
	v_fma_f32 v247, v247, s28, v195
	v_mul_f32_e32 v226, 0x4b800000, v222
	    v_mul_f32_e32 v227, 0x4b800000, v223
	    v_cmp_gt_f32_e64 s[4:5], s54, v222
	    v_cmp_gt_f32_e32 vcc, s54, v223
	    s_nop 1
	    v_cndmask_b32_e64 v222, v222, v226, s[4:5]
	    v_cndmask_b32_e32 v223, v223, v227, vcc
	    v_rsq_f32_e32 v222, v222
	    v_rsq_f32_e32 v223, v223
	    s_nop 0
	    v_mul_f32_e32 v226, 0x45800000, v222
	    v_mul_f32_e32 v227, 0x45800000, v223
	    v_cndmask_b32_e64 v222, v222, v226, s[4:5]
	    v_cndmask_b32_e32 v223, v223, v227, vcc
	    v_mul_f32_e32 v220, v222, v220
	    v_mul_f32_e32 v221, v223, v221
	    v_mul_f32_e32 v220, v184, v220
	    v_mul_f32_e32 v221, v185, v221
	    v_bfe_u32 v226, v220, 16, 1
	    v_bfe_u32 v227, v221, 16, 1
	    v_add3_u32 v220, v220, v226, s55
	    v_add3_u32 v221, v221, v227, s55
	    v_perm_b32 v21, v221, v220, v194
	    global_store_dword v[200:201], v21, off
	v_mul_f32_e32 v234, 0x4b800000, v230
	    v_mul_f32_e32 v235, 0x4b800000, v231
	    v_cmp_gt_f32_e64 s[4:5], s54, v230
	    v_cmp_gt_f32_e32 vcc, s54, v231
	    s_nop 1
	    v_cndmask_b32_e64 v230, v230, v234, s[4:5]
	    v_cndmask_b32_e32 v231, v231, v235, vcc
	    v_rsq_f32_e32 v230, v230
	    v_rsq_f32_e32 v231, v231
	    s_nop 0
	    v_mul_f32_e32 v234, 0x45800000, v230
	    v_mul_f32_e32 v235, 0x45800000, v231
	    v_cndmask_b32_e64 v230, v230, v234, s[4:5]
	    v_cndmask_b32_e32 v231, v231, v235, vcc
	    v_mul_f32_e32 v228, v230, v228
	    v_mul_f32_e32 v229, v231, v229
	    v_mul_f32_e32 v228, v184, v228
	    v_mul_f32_e32 v229, v185, v229
	    v_bfe_u32 v234, v228, 16, 1
	    v_bfe_u32 v235, v229, 16, 1
	    v_add3_u32 v228, v228, v234, s55
	    v_add3_u32 v229, v229, v235, s55
	    v_perm_b32 v22, v229, v228, v194
	    global_store_dword v[202:203], v22, off
	v_mul_f32_e32 v242, 0x4b800000, v238
	    v_mul_f32_e32 v243, 0x4b800000, v239
	    v_cmp_gt_f32_e64 s[4:5], s54, v238
	    v_cmp_gt_f32_e32 vcc, s54, v239
	    s_nop 1
	    v_cndmask_b32_e64 v238, v238, v242, s[4:5]
	    v_cndmask_b32_e32 v239, v239, v243, vcc
	    v_rsq_f32_e32 v238, v238
	    v_rsq_f32_e32 v239, v239
	    s_nop 0
	    v_mul_f32_e32 v242, 0x45800000, v238
	    v_mul_f32_e32 v243, 0x45800000, v239
	    v_cndmask_b32_e64 v238, v238, v242, s[4:5]
	    v_cndmask_b32_e32 v239, v239, v243, vcc
	    v_mul_f32_e32 v236, v238, v236
	    v_mul_f32_e32 v237, v239, v237
	    v_mul_f32_e32 v236, v184, v236
	    v_mul_f32_e32 v237, v185, v237
	    v_bfe_u32 v242, v236, 16, 1
	    v_bfe_u32 v243, v237, 16, 1
	    v_add3_u32 v236, v236, v242, s55
	    v_add3_u32 v237, v237, v243, s55
	    v_perm_b32 v19, v237, v236, v194
	    global_store_dword v[200:201], v19, off offset:256
	v_mul_f32_e32 v250, 0x4b800000, v246
	    v_mul_f32_e32 v251, 0x4b800000, v247
	    v_cmp_gt_f32_e64 s[4:5], s54, v246
	    v_cmp_gt_f32_e32 vcc, s54, v247
	    s_nop 1
	    v_cndmask_b32_e64 v246, v246, v250, s[4:5]
	    v_cndmask_b32_e32 v247, v247, v251, vcc
	    v_rsq_f32_e32 v246, v246
	    v_rsq_f32_e32 v247, v247
	    s_nop 0
	    v_mul_f32_e32 v250, 0x45800000, v246
	    v_mul_f32_e32 v251, 0x45800000, v247
	    v_cndmask_b32_e64 v246, v246, v250, s[4:5]
	    v_cndmask_b32_e32 v247, v247, v251, vcc
	    v_mul_f32_e32 v244, v246, v244
	    v_mul_f32_e32 v245, v247, v245
	    v_mul_f32_e32 v244, v184, v244
	    v_mul_f32_e32 v245, v185, v245
	    v_bfe_u32 v250, v244, 16, 1
	    v_bfe_u32 v251, v245, 16, 1
	    v_add3_u32 v244, v244, v250, s55
	    v_add3_u32 v245, v245, v251, s55
	    v_perm_b32 v20, v245, v244, v194
	    global_store_dword v[202:203], v20, off offset:256
	s_waitcnt vmcnt(12)
; __device__ __forceinline__ float bf2f(unsigned short u) { return __uint_as_float((unsigned)u << 16); }
; __device__ __forceinline__ void knorm_item(const KArgs& a, int l, int item, int wave, int lane) {
;     ...
;         for (int i = 0; i < 16; ++i) { const int task = item * 1024 + wave * 128 + r0 + i, row = task >> 2, which = (task >> 1) & 1, g = task & 1;
;             v[i] = bf2f(Z[(size_t)row * ZW + (which ? ZC_KW : ZC_KS) + g * 64 + lane]); }
; #pragma unroll
;         for (int i = 0; i < 16; ++i) { const int task = item * 1024 + wave * 128 + r0 + i, row = task >> 2, which = (task >> 1) & 1, g = task & 1;
;             const float rstd = rsqrtf(wave_sum(v[i] * v[i]) * (1.f / 64.f) + EPS);
	v_lshlrev_b32_e32 v220, 16, v17
	v_and_b32_e32 v221, 0xffff0000, v17
	v_lshlrev_b32_e32 v228, 16, v18
	v_and_b32_e32 v229, 0xffff0000, v18
	v_lshlrev_b32_e32 v236, 16, v15
	v_and_b32_e32 v237, 0xffff0000, v15
	v_lshlrev_b32_e32 v244, 16, v16
	v_and_b32_e32 v245, 0xffff0000, v16
	v_mul_f32_e32 v224, v220, v220
	v_mul_f32_e32 v225, v221, v221
	v_mul_f32_e32 v232, v228, v228
	v_mul_f32_e32 v233, v229, v229
	v_mul_f32_e32 v240, v236, v236
	v_mul_f32_e32 v241, v237, v237
	v_mul_f32_e32 v248, v244, v244
	v_mul_f32_e32 v249, v245, v245
	v_fma_f32 v222, v220, v220, v225
	v_fma_f32 v223, v221, v221, v224
	v_fma_f32 v230, v228, v228, v233
	v_fma_f32 v231, v229, v229, v232
	v_fma_f32 v238, v236, v236, v241
	v_fma_f32 v239, v237, v237, v240
	v_fma_f32 v246, v244, v244, v249
	v_fma_f32 v247, v245, v245, v248
	v_add_f32_dpp v222, v222, v222 quad_perm:[1,0,3,2] row_mask:0xf bank_mask:0xf
	v_add_f32_dpp v223, v223, v223 quad_perm:[1,0,3,2] row_mask:0xf bank_mask:0xf
	v_add_f32_dpp v230, v230, v230 quad_perm:[1,0,3,2] row_mask:0xf bank_mask:0xf
	v_add_f32_dpp v231, v231, v231 quad_perm:[1,0,3,2] row_mask:0xf bank_mask:0xf
	v_add_f32_dpp v238, v238, v238 quad_perm:[1,0,3,2] row_mask:0xf bank_mask:0xf
	v_add_f32_dpp v239, v239, v239 quad_perm:[1,0,3,2] row_mask:0xf bank_mask:0xf
	v_add_f32_dpp v246, v246, v246 quad_perm:[1,0,3,2] row_mask:0xf bank_mask:0xf
	v_add_f32_dpp v247, v247, v247 quad_perm:[1,0,3,2] row_mask:0xf bank_mask:0xf
	v_add_f32_dpp v222, v222, v222 quad_perm:[2,3,0,1] row_mask:0xf bank_mask:0xf
	v_add_f32_dpp v223, v223, v223 quad_perm:[2,3,0,1] row_mask:0xf bank_mask:0xf
	v_add_f32_dpp v230, v230, v230 quad_perm:[2,3,0,1] row_mask:0xf bank_mask:0xf
	v_add_f32_dpp v231, v231, v231 quad_perm:[2,3,0,1] row_mask:0xf bank_mask:0xf
	v_add_f32_dpp v238, v238, v238 quad_perm:[2,3,0,1] row_mask:0xf bank_mask:0xf
	v_add_f32_dpp v239, v239, v239 quad_perm:[2,3,0,1] row_mask:0xf bank_mask:0xf
	v_add_f32_dpp v246, v246, v246 quad_perm:[2,3,0,1] row_mask:0xf bank_mask:0xf
	v_add_f32_dpp v247, v247, v247 quad_perm:[2,3,0,1] row_mask:0xf bank_mask:0xf
	ds_bpermute_b32 v224, v11, v222
	ds_bpermute_b32 v225, v11, v223
	ds_bpermute_b32 v232, v11, v230
	ds_bpermute_b32 v233, v11, v231
	ds_bpermute_b32 v240, v11, v238
	ds_bpermute_b32 v241, v11, v239
	ds_bpermute_b32 v248, v11, v246
	ds_bpermute_b32 v249, v11, v247
	s_waitcnt lgkmcnt(0)
	v_add_f32_e32 v222, v222, v224
	v_add_f32_e32 v223, v223, v225
	v_add_f32_e32 v230, v230, v232
	v_add_f32_e32 v231, v231, v233
	v_add_f32_e32 v238, v238, v240
	v_add_f32_e32 v239, v239, v241
	v_add_f32_e32 v246, v246, v248
	v_add_f32_e32 v247, v247, v249
	v_add_f32_dpp v222, v222, v222 row_ror:8 row_mask:0xf bank_mask:0xf
	v_add_f32_dpp v223, v223, v223 row_ror:8 row_mask:0xf bank_mask:0xf
	v_add_f32_dpp v230, v230, v230 row_ror:8 row_mask:0xf bank_mask:0xf
	v_add_f32_dpp v231, v231, v231 row_ror:8 row_mask:0xf bank_mask:0xf
	v_add_f32_dpp v238, v238, v238 row_ror:8 row_mask:0xf bank_mask:0xf
	v_add_f32_dpp v239, v239, v239 row_ror:8 row_mask:0xf bank_mask:0xf
	v_add_f32_dpp v246, v246, v246 row_ror:8 row_mask:0xf bank_mask:0xf
	v_add_f32_dpp v247, v247, v247 row_ror:8 row_mask:0xf bank_mask:0xf
	ds_bpermute_b32 v224, v13, v222
	ds_bpermute_b32 v225, v13, v223
	ds_bpermute_b32 v232, v13, v230
	ds_bpermute_b32 v233, v13, v231
	ds_bpermute_b32 v240, v13, v238
	ds_bpermute_b32 v241, v13, v239
	ds_bpermute_b32 v248, v13, v246
	ds_bpermute_b32 v249, v13, v247
	s_waitcnt lgkmcnt(0)
; __device__ __forceinline__ unsigned f2bf(float f) { unsigned u = __float_as_uint(f); return (u + 0x7fffu + ((u >> 16) & 1u)) >> 16; }
; __device__ __forceinline__ void knorm_item(const KArgs& a, int l, int item, int wave, int lane) {
;     ...
;     for (int r0 = 0; r0 < 128; r0 += 16) {
;     ...
;             const float rstd = rsqrtf(wave_sum(v[i] * v[i]) * (1.f / 64.f) + EPS);
;             bf16_t* dst = (bf16_t*)(a.ws + (which ? WS_KWN : WS_KSN));
;             dst[(size_t)row * 128 + g * 64 + lane] = (bf16_t)f2bf(v[i] * rstd * kg); }
	v_add_f32_e32 v222, v222, v224
	v_add_f32_e32 v223, v223, v225
	v_add_f32_e32 v230, v230, v232
	v_add_f32_e32 v231, v231, v233
	v_add_f32_e32 v238, v238, v240
	v_add_f32_e32 v239, v239, v241
	v_add_f32_e32 v246, v246, v248
	v_add_f32_e32 v247, v247, v249
	v_fma_f32 v222, v222, s28, v195
	v_fma_f32 v223, v223, s28, v195
	v_fma_f32 v230, v230, s28, v195
	v_fma_f32 v231, v231, s28, v195
	v_fma_f32 v238, v238, s28, v195
	v_fma_f32 v239, v239, s28, v195
	v_fma_f32 v246, v246, s28, v195
	v_fma_f32 v247, v247, s28, v195
	v_mul_f32_e32 v226, 0x4b800000, v222
	    v_mul_f32_e32 v227, 0x4b800000, v223
	    v_cmp_gt_f32_e64 s[4:5], s54, v222
	    v_cmp_gt_f32_e32 vcc, s54, v223
	    s_nop 1
	    v_cndmask_b32_e64 v222, v222, v226, s[4:5]
	    v_cndmask_b32_e32 v223, v223, v227, vcc
	    v_rsq_f32_e32 v222, v222
	    v_rsq_f32_e32 v223, v223
	    s_nop 0
	    v_mul_f32_e32 v226, 0x45800000, v222
	    v_mul_f32_e32 v227, 0x45800000, v223
	    v_cndmask_b32_e64 v222, v222, v226, s[4:5]
	    v_cndmask_b32_e32 v223, v223, v227, vcc
	    v_mul_f32_e32 v220, v222, v220
	    v_mul_f32_e32 v221, v223, v221
	    v_mul_f32_e32 v220, v184, v220
	    v_mul_f32_e32 v221, v185, v221
	    v_bfe_u32 v226, v220, 16, 1
	    v_bfe_u32 v227, v221, 16, 1
	    v_add3_u32 v220, v220, v226, s55
	    v_add3_u32 v221, v221, v227, s55
	    v_perm_b32 v17, v221, v220, v194
	    global_store_dword v[200:201], v17, off offset:512
	v_mul_f32_e32 v234, 0x4b800000, v230
	    v_mul_f32_e32 v235, 0x4b800000, v231
	    v_cmp_gt_f32_e64 s[4:5], s54, v230
	    v_cmp_gt_f32_e32 vcc, s54, v231
	    s_nop 1
	    v_cndmask_b32_e64 v230, v230, v234, s[4:5]
	    v_cndmask_b32_e32 v231, v231, v235, vcc
	    v_rsq_f32_e32 v230, v230
	    v_rsq_f32_e32 v231, v231
	    s_nop 0
	    v_mul_f32_e32 v234, 0x45800000, v230
	    v_mul_f32_e32 v235, 0x45800000, v231
	    v_cndmask_b32_e64 v230, v230, v234, s[4:5]
	    v_cndmask_b32_e32 v231, v231, v235, vcc
	    v_mul_f32_e32 v228, v230, v228
	    v_mul_f32_e32 v229, v231, v229
	    v_mul_f32_e32 v228, v184, v228
	    v_mul_f32_e32 v229, v185, v229
	    v_bfe_u32 v234, v228, 16, 1
	    v_bfe_u32 v235, v229, 16, 1
	    v_add3_u32 v228, v228, v234, s55
	    v_add3_u32 v229, v229, v235, s55
	    v_perm_b32 v18, v229, v228, v194
	    global_store_dword v[202:203], v18, off offset:512
	v_mul_f32_e32 v242, 0x4b800000, v238
	    v_mul_f32_e32 v243, 0x4b800000, v239
	    v_cmp_gt_f32_e64 s[4:5], s54, v238
	    v_cmp_gt_f32_e32 vcc, s54, v239
	    s_nop 1
	    v_cndmask_b32_e64 v238, v238, v242, s[4:5]
	    v_cndmask_b32_e32 v239, v239, v243, vcc
	    v_rsq_f32_e32 v238, v238
	    v_rsq_f32_e32 v239, v239
	    s_nop 0
	    v_mul_f32_e32 v242, 0x45800000, v238
	    v_mul_f32_e32 v243, 0x45800000, v239
	    v_cndmask_b32_e64 v238, v238, v242, s[4:5]
	    v_cndmask_b32_e32 v239, v239, v243, vcc
	    v_mul_f32_e32 v236, v238, v236
	    v_mul_f32_e32 v237, v239, v237
	    v_mul_f32_e32 v236, v184, v236
	    v_mul_f32_e32 v237, v185, v237
	    v_bfe_u32 v242, v236, 16, 1
	    v_bfe_u32 v243, v237, 16, 1
	    v_add3_u32 v236, v236, v242, s55
	    v_add3_u32 v237, v237, v243, s55
	    v_perm_b32 v15, v237, v236, v194
	    global_store_dword v[200:201], v15, off offset:768
	v_mul_f32_e32 v250, 0x4b800000, v246
	    v_mul_f32_e32 v251, 0x4b800000, v247
	    v_cmp_gt_f32_e64 s[4:5], s54, v246
	    v_cmp_gt_f32_e32 vcc, s54, v247
	    s_nop 1
	    v_cndmask_b32_e64 v246, v246, v250, s[4:5]
	    v_cndmask_b32_e32 v247, v247, v251, vcc
	    v_rsq_f32_e32 v246, v246
	    v_rsq_f32_e32 v247, v247
	    s_nop 0
	    v_mul_f32_e32 v250, 0x45800000, v246
	    v_mul_f32_e32 v251, 0x45800000, v247
	    v_cndmask_b32_e64 v246, v246, v250, s[4:5]
	    v_cndmask_b32_e32 v247, v247, v251, vcc
	    v_mul_f32_e32 v244, v246, v244
	    v_mul_f32_e32 v245, v247, v245
	    v_mul_f32_e32 v244, v184, v244
	    v_mul_f32_e32 v245, v185, v245
	    v_bfe_u32 v250, v244, 16, 1
	    v_bfe_u32 v251, v245, 16, 1
	    v_add3_u32 v244, v244, v250, s55
	    v_add3_u32 v245, v245, v251, s55
	    v_perm_b32 v16, v245, v244, v194
	    global_store_dword v[202:203], v16, off offset:768
	s_add_i32 s63, s63, 32
	s_cmpk_gt_u32 s63, 0x6f
	s_cbranch_scc0 .LBB0_1038
	s_mov_b64 s[0:1], 0
